# LayerNorm phases: second-pass per-column parameter loads issued together at the start of the pass (one wait) instead of one pair per chunk behind vmcnt(0)
# speedup vs baseline: 1.0063x; 1.0041x over previous
; __device__ __forceinline__ void phase_ln(const Params& p, int s) {
;     ...
;     for (int row = blockIdx.x * 8 + wid; row < 16384; row += gridDim.x * 8) {
;         const int b = row >> 12; const float* gate = mods + (size_t)s * 24576 + b * 6144 + 4096;
;         f32x4 v[8]; float sum = 0.f;
; #pragma unroll
;         for (int i = 0; i < 8; ++i) { const int c = i * 256 + lane * 4;
;             const f32x4 xv = __builtin_nontemporal_load((const f32x4*)(xin + (size_t)row * 2048 + c)), gt = *(const f32x4*)(gate + c); const f16x4 yv = __builtin_nontemporal_load((const f16x4*)(Y + (size_t)row * 2048 + c));
; #pragma unroll
;             for (int j = 0; j < 4; ++j) { v[i][j] = ALPHA_C * xv[j] + (1.0f + gt[j]) * (float)yv[j]; sum += v[i][j]; } }
.LBB0_1709:
	v_ashrrev_i32_e32 v50, 12, v8
	v_ashrrev_i32_e32 v9, 31, v8
	v_mul_i32_i24_e32 v52, 0x1800, v50
	v_lshlrev_b64 v[50:51], 13, v[8:9]
	v_lshlrev_b64 v[60:61], 12, v[8:9]
	v_ashrrev_i32_e32 v53, 31, v52
	v_lshl_add_u64 v[54:55], s[36:37], 0, v[50:51]
	v_lshl_add_u64 v[106:107], v[32:33], 0, v[60:61]
	v_lshlrev_b64 v[52:53], 2, v[52:53]
	global_load_dwordx4 v[0:3], v[12:13], off
	global_load_dwordx4 v[4:7], v[14:15], off
	v_lshl_add_u64 v[58:59], v[54:55], 0, v[10:11]
	v_lshl_add_u64 v[66:67], v[54:55], 0, v[42:43]
	global_load_dwordx2 v[130:131], v[106:107], off offset:2560 nt
	global_load_dwordx2 v[132:133], v[106:107], off offset:3072 nt
	global_load_dwordx2 v[134:135], v[106:107], off offset:3584 nt
	global_load_dwordx2 v[136:137], v[106:107], off offset:512 nt
	global_load_dwordx2 v[138:139], v[106:107], off offset:1024 nt
	global_load_dwordx2 v[140:141], v[106:107], off offset:1536 nt
	global_load_dwordx2 v[142:143], v[106:107], off offset:2048 nt
	v_lshl_add_u64 v[102:103], s[70:71], 0, v[52:53]
	v_lshl_add_u64 v[98:99], v[54:55], 0, v[44:45]
	v_lshl_add_u64 v[100:101], v[54:55], 0, v[46:47]
	v_lshl_add_u64 v[54:55], v[54:55], 0, v[48:49]
	global_load_dwordx4 v[62:65], v[58:59], off nt
	global_load_dwordx4 v[68:71], v[58:59], off offset:1024 nt
	global_load_dwordx4 v[74:77], v[58:59], off offset:2048 nt
	global_load_dwordx4 v[78:81], v[58:59], off offset:3072 nt
	global_load_dwordx4 v[82:85], v[66:67], off nt
	global_load_dwordx4 v[86:89], v[98:99], off nt
	global_load_dwordx4 v[90:93], v[100:101], off nt
	global_load_dwordx4 v[94:97], v[54:55], off nt
	v_lshl_add_u64 v[66:67], v[102:103], 0, s[10:11]
	v_lshl_add_u64 v[102:103], v[66:67], 0, v[10:11]
	v_lshl_add_u64 v[110:111], v[66:67], 0, v[36:37]
	v_lshl_add_u64 v[114:115], v[66:67], 0, v[38:39]
	v_lshl_add_u64 v[118:119], v[66:67], 0, v[40:41]
	v_lshl_add_u64 v[122:123], v[66:67], 0, v[42:43]
	v_lshl_add_u64 v[126:127], v[66:67], 0, v[44:45]
	v_lshl_add_u64 v[108:109], v[66:67], 0, v[46:47]
	v_lshl_add_u64 v[98:99], v[66:67], 0, v[48:49]
	global_load_dwordx4 v[98:101], v[98:99], off
	s_nop 0
	global_load_dwordx4 v[102:105], v[102:103], off
	s_nop 0
	global_load_dwordx2 v[144:145], v[106:107], off nt
	s_nop 0
	global_load_dwordx4 v[106:109], v[108:109], off
	s_nop 0
	global_load_dwordx4 v[110:113], v[110:111], off
	s_nop 0
	global_load_dwordx4 v[114:117], v[114:115], off
	s_nop 0
	global_load_dwordx4 v[118:121], v[118:119], off
	s_nop 0
	global_load_dwordx4 v[122:125], v[122:123], off
	s_nop 0
	global_load_dwordx4 v[126:129], v[126:127], off
	v_lshl_add_u64 v[50:51], s[80:81], 0, v[50:51]
	v_lshl_add_u64 v[52:53], s[4:5], 0, v[52:53]
	v_lshl_add_u64 v[56:57], v[50:51], 0, v[10:11]
	v_lshl_add_u64 v[54:55], v[52:53], 0, s[14:15]
	v_lshl_add_u64 v[66:67], v[54:55], 0, v[10:11]
	v_lshl_add_u64 v[58:59], v[52:53], 0, v[10:11]
	v_add_u32_e32 v8, s2, v8
	s_waitcnt vmcnt(23)
	v_cvt_f32_f16_e32 v160, v130
	s_waitcnt vmcnt(22)
	v_cvt_f32_f16_e32 v162, v132
	s_waitcnt vmcnt(21)
	v_cvt_f32_f16_e32 v148, v134
	v_cvt_f32_f16_sdwa v149, v134 dst_sel:DWORD dst_unused:UNUSED_PAD src0_sel:WORD_1
	v_cvt_f32_f16_e32 v146, v135
	v_cvt_f32_f16_sdwa v147, v135 dst_sel:DWORD dst_unused:UNUSED_PAD src0_sel:WORD_1
	v_cvt_f32_f16_e32 v134, v133
	v_cvt_f32_f16_sdwa v135, v133 dst_sel:DWORD dst_unused:UNUSED_PAD src0_sel:WORD_1
	v_cvt_f32_f16_sdwa v163, v132 dst_sel:DWORD dst_unused:UNUSED_PAD src0_sel:WORD_1
	s_waitcnt vmcnt(20)
	v_cvt_f32_f16_e32 v150, v136
	v_cvt_f32_f16_sdwa v151, v136 dst_sel:DWORD dst_unused:UNUSED_PAD src0_sel:WORD_1
	v_cvt_f32_f16_e32 v136, v137
	v_cvt_f32_f16_sdwa v137, v137 dst_sel:DWORD dst_unused:UNUSED_PAD src0_sel:WORD_1
	s_waitcnt vmcnt(8)
	v_pk_add_f32 v[98:99], v[98:99], 1.0 op_sel_hi:[1,0]
	s_waitcnt vmcnt(7)
	v_pk_add_f32 v[102:103], v[102:103], 1.0 op_sel_hi:[1,0]
	s_waitcnt vmcnt(6)
	v_cvt_f32_f16_e32 v132, v144
	v_cvt_f32_f16_sdwa v133, v144 dst_sel:DWORD dst_unused:UNUSED_PAD src0_sel:WORD_1
	v_cvt_f32_f16_e32 v144, v145
	v_cvt_f32_f16_sdwa v145, v145 dst_sel:DWORD dst_unused:UNUSED_PAD src0_sel:WORD_1
	v_pk_mul_f32 v[98:99], v[98:99], v[148:149]
	v_pk_add_f32 v[100:101], v[100:101], 1.0 op_sel_hi:[1,0]
	v_pk_fma_f32 v[94:95], v[94:95], s[12:13], v[98:99] op_sel_hi:[1,0,1]
	v_pk_mul_f32 v[98:99], v[102:103], v[132:133]
	v_pk_add_f32 v[104:105], v[104:105], 1.0 op_sel_hi:[1,0]
	v_pk_mul_f32 v[100:101], v[100:101], v[146:147]
	v_pk_fma_f32 v[62:63], v[62:63], s[12:13], v[98:99] op_sel_hi:[1,0,1]
	v_pk_fma_f32 v[96:97], v[96:97], s[12:13], v[100:101] op_sel_hi:[1,0,1]
	v_pk_mul_f32 v[100:101], v[104:105], v[144:145]
	v_add_f32_e32 v9, 0, v62
	s_waitcnt vmcnt(4)
	v_pk_add_f32 v[110:111], v[110:111], 1.0 op_sel_hi:[1,0]
	v_pk_fma_f32 v[64:65], v[64:65], s[12:13], v[100:101] op_sel_hi:[1,0,1]
	v_add_f32_e32 v9, v63, v9
	v_cvt_f32_f16_e32 v154, v138
	v_cvt_f32_f16_sdwa v155, v138 dst_sel:DWORD dst_unused:UNUSED_PAD src0_sel:WORD_1
	v_pk_mul_f32 v[110:111], v[110:111], v[150:151]
	v_add_f32_e32 v9, v64, v9
	v_pk_add_f32 v[112:113], v[112:113], 1.0 op_sel_hi:[1,0]
	v_pk_fma_f32 v[68:69], v[68:69], s[12:13], v[110:111] op_sel_hi:[1,0,1]
	v_add_f32_e32 v9, v65, v9
	v_cvt_f32_f16_e32 v138, v139
	v_cvt_f32_f16_sdwa v139, v139 dst_sel:DWORD dst_unused:UNUSED_PAD src0_sel:WORD_1
	v_pk_mul_f32 v[112:113], v[112:113], v[136:137]
	v_add_f32_e32 v9, v68, v9
	s_waitcnt vmcnt(3)
; __device__ __forceinline__ void phase_ln(const Params& p, int s) {
;     ...
;             for (int j = 0; j < 4; ++j) { v[i][j] = ALPHA_C * xv[j] + (1.0f + gt[j]) * (float)yv[j]; sum += v[i][j]; } }
;         sum = wave_sum(sum); const float mean = sum * (1.0f / 2048.0f); float sq = 0.f;
; #pragma unroll
;         for (int i = 0; i < 8; ++i)
; #pragma unroll
;             for (int j = 0; j < 4; ++j) { const float d = v[i][j] - mean; sq += d * d; }
;         sq = wave_sum(sq); const float rs = rsqrtf(sq * (1.0f / 2048.0f) + 1e-5f);
	v_pk_add_f32 v[114:115], v[114:115], 1.0 op_sel_hi:[1,0]
	v_pk_fma_f32 v[70:71], v[70:71], s[12:13], v[112:113] op_sel_hi:[1,0,1]
	v_add_f32_e32 v9, v69, v9
	v_cvt_f32_f16_e32 v156, v140
	v_cvt_f32_f16_sdwa v157, v140 dst_sel:DWORD dst_unused:UNUSED_PAD src0_sel:WORD_1
	v_pk_mul_f32 v[114:115], v[114:115], v[154:155]
	v_add_f32_e32 v9, v70, v9
	v_pk_add_f32 v[116:117], v[116:117], 1.0 op_sel_hi:[1,0]
	v_pk_fma_f32 v[74:75], v[74:75], s[12:13], v[114:115] op_sel_hi:[1,0,1]
	v_add_f32_e32 v9, v71, v9
	v_cvt_f32_f16_e32 v140, v141
	v_cvt_f32_f16_sdwa v141, v141 dst_sel:DWORD dst_unused:UNUSED_PAD src0_sel:WORD_1
	v_pk_mul_f32 v[116:117], v[116:117], v[138:139]
	v_add_f32_e32 v9, v74, v9
	s_waitcnt vmcnt(2)
	v_pk_add_f32 v[118:119], v[118:119], 1.0 op_sel_hi:[1,0]
	v_pk_fma_f32 v[76:77], v[76:77], s[12:13], v[116:117] op_sel_hi:[1,0,1]
	v_add_f32_e32 v9, v75, v9
	v_cvt_f32_f16_e32 v158, v142
	v_cvt_f32_f16_sdwa v159, v142 dst_sel:DWORD dst_unused:UNUSED_PAD src0_sel:WORD_1
	v_pk_mul_f32 v[118:119], v[118:119], v[156:157]
	v_add_f32_e32 v9, v76, v9
	v_pk_add_f32 v[120:121], v[120:121], 1.0 op_sel_hi:[1,0]
	v_pk_fma_f32 v[78:79], v[78:79], s[12:13], v[118:119] op_sel_hi:[1,0,1]
	v_add_f32_e32 v9, v77, v9
	v_cvt_f32_f16_e32 v142, v143
	v_cvt_f32_f16_sdwa v143, v143 dst_sel:DWORD dst_unused:UNUSED_PAD src0_sel:WORD_1
	v_pk_mul_f32 v[120:121], v[120:121], v[140:141]
	v_add_f32_e32 v9, v78, v9
	s_waitcnt vmcnt(1)
	v_pk_add_f32 v[122:123], v[122:123], 1.0 op_sel_hi:[1,0]
	v_pk_fma_f32 v[80:81], v[80:81], s[12:13], v[120:121] op_sel_hi:[1,0,1]
	v_add_f32_e32 v9, v79, v9
	v_cvt_f32_f16_sdwa v161, v130 dst_sel:DWORD dst_unused:UNUSED_PAD src0_sel:WORD_1
	v_pk_mul_f32 v[122:123], v[122:123], v[158:159]
	v_add_f32_e32 v9, v80, v9
	v_pk_add_f32 v[124:125], v[124:125], 1.0 op_sel_hi:[1,0]
	v_pk_fma_f32 v[82:83], v[82:83], s[12:13], v[122:123] op_sel_hi:[1,0,1]
	v_add_f32_e32 v9, v81, v9
	v_cvt_f32_f16_e32 v130, v131
	v_cvt_f32_f16_sdwa v131, v131 dst_sel:DWORD dst_unused:UNUSED_PAD src0_sel:WORD_1
	v_pk_mul_f32 v[124:125], v[124:125], v[142:143]
	v_add_f32_e32 v9, v82, v9
	s_waitcnt vmcnt(0)
	v_pk_add_f32 v[126:127], v[126:127], 1.0 op_sel_hi:[1,0]
	v_pk_fma_f32 v[84:85], v[84:85], s[12:13], v[124:125] op_sel_hi:[1,0,1]
	v_add_f32_e32 v9, v83, v9
	v_pk_mul_f32 v[126:127], v[126:127], v[160:161]
	v_add_f32_e32 v9, v84, v9
	v_pk_add_f32 v[128:129], v[128:129], 1.0 op_sel_hi:[1,0]
	v_pk_fma_f32 v[86:87], v[86:87], s[12:13], v[126:127] op_sel_hi:[1,0,1]
	v_add_f32_e32 v9, v85, v9
	v_pk_mul_f32 v[128:129], v[128:129], v[130:131]
	v_add_f32_e32 v9, v86, v9
	v_pk_add_f32 v[106:107], v[106:107], 1.0 op_sel_hi:[1,0]
	v_pk_fma_f32 v[88:89], v[88:89], s[12:13], v[128:129] op_sel_hi:[1,0,1]
	v_add_f32_e32 v9, v87, v9
	v_pk_mul_f32 v[106:107], v[106:107], v[162:163]
	v_add_f32_e32 v9, v88, v9
	v_pk_add_f32 v[108:109], v[108:109], 1.0 op_sel_hi:[1,0]
	v_pk_fma_f32 v[90:91], v[90:91], s[12:13], v[106:107] op_sel_hi:[1,0,1]
	v_add_f32_e32 v9, v89, v9
	v_pk_mul_f32 v[108:109], v[108:109], v[134:135]
	v_add_f32_e32 v9, v90, v9
	v_pk_fma_f32 v[92:93], v[92:93], s[12:13], v[108:109] op_sel_hi:[1,0,1]
	v_add_f32_e32 v9, v91, v9
	v_add_f32_e32 v9, v92, v9
	v_add_f32_e32 v9, v93, v9
	v_add_f32_e32 v9, v94, v9
	v_add_f32_e32 v9, v95, v9
	v_add_f32_e32 v9, v96, v9
	v_add_f32_e32 v9, v97, v9
	s_nop 1
	v_add_f32_dpp v9, v9, v9 quad_perm:[1,0,3,2] row_mask:0xf bank_mask:0xf bound_ctrl:1
	s_nop 1
	v_add_f32_dpp v9, v9, v9 quad_perm:[2,3,0,1] row_mask:0xf bank_mask:0xf bound_ctrl:1
	s_nop 1
	v_add_f32_dpp v9, v9, v9 row_half_mirror row_mask:0xf bank_mask:0xf bound_ctrl:1
	s_nop 1
	v_add_f32_dpp v9, v9, v9 row_mirror row_mask:0xf bank_mask:0xf bound_ctrl:1
	s_nop 0
	v_readlane_b32 s20, v9, 16
	v_readlane_b32 s21, v9, 48
	v_readlane_b32 s16, v9, 0
	v_readlane_b32 s17, v9, 32
	v_mov_b32_e32 v98, s20
	v_mov_b32_e32 v99, s21
	v_pk_add_f32 v[98:99], s[16:17], v[98:99]
	s_nop 0
	v_add_f32_e32 v9, v98, v99
	v_mul_f32_e32 v72, 0x3a000000, v9
	v_pk_add_f32 v[98:99], v[62:63], v[72:73] op_sel_hi:[1,0] neg_lo:[0,1] neg_hi:[0,1]
	v_pk_add_f32 v[100:101], v[64:65], v[72:73] op_sel_hi:[1,0] neg_lo:[0,1] neg_hi:[0,1]
	v_pk_add_f32 v[110:111], v[78:79], v[72:73] op_sel_hi:[1,0] neg_lo:[0,1] neg_hi:[0,1]
	v_pk_mul_f32 v[78:79], v[98:99], v[98:99]
	v_pk_add_f32 v[112:113], v[80:81], v[72:73] op_sel_hi:[1,0] neg_lo:[0,1] neg_hi:[0,1]
	v_pk_mul_f32 v[80:81], v[100:101], v[100:101]
	v_add_f32_e32 v9, v78, v79
	v_pk_add_f32 v[102:103], v[68:69], v[72:73] op_sel_hi:[1,0] neg_lo:[0,1] neg_hi:[0,1]
	v_add_f32_e32 v9, v80, v9
	v_pk_add_f32 v[114:115], v[82:83], v[72:73] op_sel_hi:[1,0] neg_lo:[0,1] neg_hi:[0,1]
	v_pk_mul_f32 v[82:83], v[102:103], v[102:103]
	v_add_f32_e32 v9, v81, v9
	v_pk_add_f32 v[104:105], v[70:71], v[72:73] op_sel_hi:[1,0] neg_lo:[0,1] neg_hi:[0,1]
	v_add_f32_e32 v9, v82, v9
	v_pk_add_f32 v[116:117], v[84:85], v[72:73] op_sel_hi:[1,0] neg_lo:[0,1] neg_hi:[0,1]
	v_pk_mul_f32 v[84:85], v[104:105], v[104:105]
	v_add_f32_e32 v9, v83, v9
	v_pk_add_f32 v[106:107], v[74:75], v[72:73] op_sel_hi:[1,0] neg_lo:[0,1] neg_hi:[0,1]
	v_add_f32_e32 v9, v84, v9
	v_pk_add_f32 v[74:75], v[86:87], v[72:73] op_sel_hi:[1,0] neg_lo:[0,1] neg_hi:[0,1]
	v_pk_mul_f32 v[86:87], v[106:107], v[106:107]
	v_add_f32_e32 v9, v85, v9
	v_pk_add_f32 v[108:109], v[76:77], v[72:73] op_sel_hi:[1,0] neg_lo:[0,1] neg_hi:[0,1]
	v_add_f32_e32 v9, v86, v9
	v_pk_add_f32 v[76:77], v[88:89], v[72:73] op_sel_hi:[1,0] neg_lo:[0,1] neg_hi:[0,1]
	v_pk_mul_f32 v[88:89], v[108:109], v[108:109]
	v_add_f32_e32 v9, v87, v9
	v_add_f32_e32 v9, v88, v9
	v_pk_add_f32 v[68:69], v[90:91], v[72:73] op_sel_hi:[1,0] neg_lo:[0,1] neg_hi:[0,1]
; __device__ __forceinline__ unsigned cvt_pk_bf16(float lo, float hi) { unsigned r; asm volatile("v_cvt_pk_bf16_f32 %0, %1, %2" : "=v"(r) : "v"(lo), "v"(hi)); return r; }
; __device__ __forceinline__ void phase_ln(const Params& p, int s) {
;     ...
;         sq = wave_sum(sq); const float rs = rsqrtf(sq * (1.0f / 2048.0f) + 1e-5f);
; #pragma unroll
;         for (int i = 0; i < 8; ++i) { const int c = i * 256 + lane * 4; const f32x4 g4 = *(const f32x4*)(lg + c), b4 = *(const f32x4*)(lb + c); f32x4 xn;
; #pragma unroll
;             for (int j = 0; j < 4; ++j) xn[j] = (v[i][j] - mean) * rs * g4[j] + b4[j];
;             __builtin_nontemporal_store(xn, (f32x4*)(p.out + (size_t)row * 2048 + c));
;             if (s < 3) { const float* mn = mods + (size_t)(s + 1) * 24576 + b * 6144; const f32x4 sh = *(const f32x4*)(mn + c), scl = *(const f32x4*)(mn + 2048 + c);
;                 u32x2 o; o[0] = cvt_pk_bf16(xn[0] * (1.f + scl[0]) + sh[0], xn[1] * (1.f + scl[1]) + sh[1]); o[1] = cvt_pk_bf16(xn[2] * (1.f + scl[2]) + sh[2], xn[3] * (1.f + scl[3]) + sh[3]);
	v_pk_mul_f32 v[90:91], v[110:111], v[110:111]
	v_add_f32_e32 v9, v89, v9
	v_add_f32_e32 v9, v90, v9
	v_pk_add_f32 v[70:71], v[92:93], v[72:73] op_sel_hi:[1,0] neg_lo:[0,1] neg_hi:[0,1]
	v_pk_mul_f32 v[92:93], v[112:113], v[112:113]
	v_add_f32_e32 v9, v91, v9
	v_add_f32_e32 v9, v92, v9
	v_pk_add_f32 v[62:63], v[94:95], v[72:73] op_sel_hi:[1,0] neg_lo:[0,1] neg_hi:[0,1]
	v_pk_mul_f32 v[94:95], v[114:115], v[114:115]
	v_add_f32_e32 v9, v93, v9
	v_add_f32_e32 v9, v94, v9
	v_pk_add_f32 v[64:65], v[96:97], v[72:73] op_sel_hi:[1,0] neg_lo:[0,1] neg_hi:[0,1]
	v_pk_mul_f32 v[96:97], v[116:117], v[116:117]
	v_add_f32_e32 v9, v95, v9
	v_add_f32_e32 v9, v96, v9
	v_pk_mul_f32 v[118:119], v[74:75], v[74:75]
	v_add_f32_e32 v9, v97, v9
	v_add_f32_e32 v9, v118, v9
	v_pk_mul_f32 v[120:121], v[76:77], v[76:77]
	v_add_f32_e32 v9, v119, v9
	v_add_f32_e32 v9, v120, v9
	v_pk_mul_f32 v[122:123], v[68:69], v[68:69]
	v_add_f32_e32 v9, v121, v9
	v_add_f32_e32 v9, v122, v9
	v_pk_mul_f32 v[124:125], v[70:71], v[70:71]
	v_add_f32_e32 v9, v123, v9
	v_add_f32_e32 v9, v124, v9
	v_pk_mul_f32 v[126:127], v[62:63], v[62:63]
	v_add_f32_e32 v9, v125, v9
	v_add_f32_e32 v9, v126, v9
	v_pk_mul_f32 v[128:129], v[64:65], v[64:65]
	v_add_f32_e32 v9, v127, v9
	v_add_f32_e32 v9, v128, v9
	v_add_f32_e32 v9, v129, v9
	s_nop 1
	v_add_f32_dpp v9, v9, v9 quad_perm:[1,0,3,2] row_mask:0xf bank_mask:0xf bound_ctrl:1
	s_nop 1
	v_add_f32_dpp v9, v9, v9 quad_perm:[2,3,0,1] row_mask:0xf bank_mask:0xf bound_ctrl:1
	s_nop 1
	v_add_f32_dpp v9, v9, v9 row_half_mirror row_mask:0xf bank_mask:0xf bound_ctrl:1
	s_nop 1
	v_add_f32_dpp v9, v9, v9 row_mirror row_mask:0xf bank_mask:0xf bound_ctrl:1
	s_nop 0
	v_readlane_b32 s20, v9, 16
	v_readlane_b32 s21, v9, 48
	v_readlane_b32 s16, v9, 0
	v_readlane_b32 s17, v9, 32
	v_mov_b32_e32 v78, s20
	v_mov_b32_e32 v79, s21
	v_pk_add_f32 v[78:79], s[16:17], v[78:79]
	s_nop 0
	v_add_f32_e32 v9, v78, v79
	v_fmamk_f32 v9, v9, 0x3a000000, v73
	v_mul_f32_e32 v72, 0x4b800000, v9
	v_cmp_gt_f32_e32 vcc, s3, v9
	s_nop 1
	v_cndmask_b32_e32 v9, v9, v72, vcc
	v_rsq_f32_e32 v9, v9
	s_nop 0
	v_mul_f32_e32 v72, 0x45800000, v9
	v_cndmask_b32_e32 v72, v9, v72, vcc
	v_pk_mul_f32 v[78:79], v[98:99], v[72:73] op_sel_hi:[1,0]
	v_pk_mul_f32 v[80:81], v[100:101], v[72:73] op_sel_hi:[1,0]
	v_pk_fma_f32 v[4:5], v[0:1], v[78:79], v[4:5]
	v_pk_fma_f32 v[6:7], v[2:3], v[80:81], v[6:7]
	global_load_dwordx4 v[86:89], v[66:67], off
	global_load_dwordx4 v[90:93], v[58:59], off
	global_load_dwordx4 v[94:97], v[12:13], off offset:1024
	global_load_dwordx4 v[98:101], v[14:15], off offset:1024
	v_lshl_add_u64 v[118:119], v[54:55], 0, v[36:37]
	global_load_dwordx4 v[118:121], v[118:119], off
	global_load_dwordx4 v[122:125], v[58:59], off offset:1024
	global_load_dwordx4 v[126:129], v[12:13], off offset:2048
	global_load_dwordx4 v[130:133], v[14:15], off offset:2048
	v_lshl_add_u64 v[134:135], v[54:55], 0, v[38:39]
	global_load_dwordx4 v[134:137], v[134:135], off
	global_load_dwordx4 v[138:141], v[58:59], off offset:2048
	global_load_dwordx4 v[142:145], v[12:13], off offset:3072
	global_load_dwordx4 v[146:149], v[14:15], off offset:3072
	v_lshl_add_u64 v[154:155], v[54:55], 0, v[40:41]
	global_load_dwordx4 v[154:157], v[154:155], off
	global_load_dwordx4 v[158:161], v[58:59], off offset:3072
	global_load_dwordx4 v[162:165], v[16:17], off
	global_load_dwordx4 v[166:169], v[18:19], off
	v_lshl_add_u64 v[172:173], v[54:55], 0, v[42:43]
	global_load_dwordx4 v[172:175], v[172:173], off
	v_lshl_add_u64 v[176:177], v[52:53], 0, v[42:43]
	global_load_dwordx4 v[176:179], v[176:177], off
	global_load_dwordx4 v[180:183], v[20:21], off
	global_load_dwordx4 v[184:187], v[22:23], off
	v_lshl_add_u64 v[188:189], v[54:55], 0, v[44:45]
	global_load_dwordx4 v[188:191], v[188:189], off
	v_lshl_add_u64 v[192:193], v[52:53], 0, v[44:45]
	global_load_dwordx4 v[192:195], v[192:193], off
	global_load_dwordx4 v[196:199], v[24:25], off
	global_load_dwordx4 v[200:203], v[26:27], off
	v_lshl_add_u64 v[204:205], v[54:55], 0, v[46:47]
	global_load_dwordx4 v[204:207], v[204:205], off
	v_lshl_add_u64 v[208:209], v[52:53], 0, v[46:47]
	global_load_dwordx4 v[208:211], v[208:209], off
	global_load_dwordx4 v[212:215], v[28:29], off
	global_load_dwordx4 v[216:219], v[30:31], off
	v_lshl_add_u64 v[220:221], v[54:55], 0, v[48:49]
	global_load_dwordx4 v[220:223], v[220:221], off
	v_lshl_add_u64 v[224:225], v[52:53], 0, v[48:49]
	global_load_dwordx4 v[224:227], v[224:225], off
	s_waitcnt vmcnt(0)
; __device__ __forceinline__ unsigned cvt_pk_bf16(float lo, float hi) { unsigned r; asm volatile("v_cvt_pk_bf16_f32 %0, %1, %2" : "=v"(r) : "v"(lo), "v"(hi)); return r; }
; __device__ __forceinline__ void phase_ln(const Params& p, int s) {
;     ...
;         for (int i = 0; i < 8; ++i) { const int c = i * 256 + lane * 4; const f32x4 g4 = *(const f32x4*)(lg + c), b4 = *(const f32x4*)(lb + c); f32x4 xn;
; #pragma unroll
;             for (int j = 0; j < 4; ++j) xn[j] = (v[i][j] - mean) * rs * g4[j] + b4[j];
;             __builtin_nontemporal_store(xn, (f32x4*)(p.out + (size_t)row * 2048 + c));
;             if (s < 3) { const float* mn = mods + (size_t)(s + 1) * 24576 + b * 6144; const f32x4 sh = *(const f32x4*)(mn + c), scl = *(const f32x4*)(mn + 2048 + c);
;                 u32x2 o; o[0] = cvt_pk_bf16(xn[0] * (1.f + scl[0]) + sh[0], xn[1] * (1.f + scl[1]) + sh[1]); o[1] = cvt_pk_bf16(xn[2] * (1.f + scl[2]) + sh[2], xn[3] * (1.f + scl[3]) + sh[3]);
;                 *(u32x2*)(H + (size_t)row * 2048 + c) = o; } }
	global_store_dwordx4 v[56:57], v[4:7], off nt
	v_mov_b32_e32 v78, v86
	v_mov_b32_e32 v79, v87
	v_mov_b32_e32 v80, v88
	v_mov_b32_e32 v81, v89
	v_mov_b32_e32 v82, v90
	v_mov_b32_e32 v83, v91
	v_mov_b32_e32 v84, v92
	v_mov_b32_e32 v85, v93
	v_lshl_add_u64 v[0:1], v[34:35], 0, v[60:61]
	v_pk_mul_f32 v[66:67], v[104:105], v[72:73] op_sel_hi:[1,0]
	v_pk_mul_f32 v[74:75], v[74:75], v[72:73] op_sel_hi:[1,0]
	v_pk_mul_f32 v[76:77], v[76:77], v[72:73] op_sel_hi:[1,0]
	v_cmp_lt_i32_e32 vcc, s13, v8
	s_or_b64 s[6:7], vcc, s[6:7]
	v_add_f32_e32 v2, 1.0, v78
	v_add_f32_e32 v3, 1.0, v79
	v_add_f32_e32 v9, 1.0, v80
	v_add_f32_e32 v60, 1.0, v81
	v_fma_f32 v2, v2, v4, v82
	v_fma_f32 v3, v3, v5, v83
	v_fma_f32 v4, v9, v6, v84
	v_fmac_f32_e32 v85, v60, v7
	v_cvt_pk_bf16_f32 v2, v2, v3
	v_cvt_pk_bf16_f32 v3, v4, v85
	global_store_dwordx2 v[0:1], v[2:3], off
	v_mov_b32_e32 v2, v94
	v_mov_b32_e32 v3, v95
	v_mov_b32_e32 v4, v96
	v_mov_b32_e32 v5, v97
	v_mov_b32_e32 v78, v98
	v_mov_b32_e32 v79, v99
	v_mov_b32_e32 v80, v100
	v_mov_b32_e32 v81, v101
	v_pk_mul_f32 v[60:61], v[102:103], v[72:73] op_sel_hi:[1,0]
	v_lshl_add_u64 v[6:7], v[54:55], 0, v[36:37]
	v_pk_fma_f32 v[2:3], v[2:3], v[60:61], v[78:79]
	v_pk_fma_f32 v[4:5], v[4:5], v[66:67], v[80:81]
	global_store_dwordx4 v[56:57], v[2:5], off offset:1024 nt
	v_mov_b32_e32 v78, v118
	v_mov_b32_e32 v79, v119
	v_mov_b32_e32 v80, v120
	v_mov_b32_e32 v81, v121
	v_mov_b32_e32 v82, v122
	v_mov_b32_e32 v83, v123
	v_mov_b32_e32 v84, v124
	v_mov_b32_e32 v85, v125
	v_pk_mul_f32 v[66:67], v[108:109], v[72:73] op_sel_hi:[1,0]
	v_add_f32_e32 v6, 1.0, v78
	v_add_f32_e32 v7, 1.0, v79
	v_add_f32_e32 v9, 1.0, v80
	v_add_f32_e32 v60, 1.0, v81
	v_fma_f32 v2, v2, v6, v82
	v_fma_f32 v3, v3, v7, v83
	v_fma_f32 v4, v4, v9, v84
	v_fmac_f32_e32 v85, v5, v60
	v_cvt_pk_bf16_f32 v2, v2, v3
	v_cvt_pk_bf16_f32 v3, v4, v85
	global_store_dwordx2 v[0:1], v[2:3], off offset:512
	v_mov_b32_e32 v2, v126
	v_mov_b32_e32 v3, v127
	v_mov_b32_e32 v4, v128
	v_mov_b32_e32 v5, v129
	v_mov_b32_e32 v78, v130
	v_mov_b32_e32 v79, v131
	v_mov_b32_e32 v80, v132
	v_mov_b32_e32 v81, v133
	v_pk_mul_f32 v[60:61], v[106:107], v[72:73] op_sel_hi:[1,0]
	v_lshl_add_u64 v[6:7], v[54:55], 0, v[38:39]
	v_pk_fma_f32 v[2:3], v[60:61], v[2:3], v[78:79]
	v_pk_fma_f32 v[4:5], v[66:67], v[4:5], v[80:81]
	global_store_dwordx4 v[56:57], v[2:5], off offset:2048 nt
	v_mov_b32_e32 v78, v134
	v_mov_b32_e32 v79, v135
	v_mov_b32_e32 v80, v136
	v_mov_b32_e32 v81, v137
	v_mov_b32_e32 v82, v138
	v_mov_b32_e32 v83, v139
	v_mov_b32_e32 v84, v140
	v_mov_b32_e32 v85, v141
	v_pk_mul_f32 v[66:67], v[112:113], v[72:73] op_sel_hi:[1,0]
	v_add_f32_e32 v6, 1.0, v78
	v_add_f32_e32 v7, 1.0, v79
	v_add_f32_e32 v9, 1.0, v80
	v_add_f32_e32 v60, 1.0, v81
	v_fma_f32 v2, v2, v6, v82
	v_fma_f32 v3, v3, v7, v83
	v_fma_f32 v4, v4, v9, v84
	v_fmac_f32_e32 v85, v5, v60
	v_cvt_pk_bf16_f32 v2, v2, v3
	v_cvt_pk_bf16_f32 v3, v4, v85
	global_store_dwordx2 v[0:1], v[2:3], off offset:1024
	v_mov_b32_e32 v2, v142
	v_mov_b32_e32 v3, v143
	v_mov_b32_e32 v4, v144
	v_mov_b32_e32 v5, v145
	v_mov_b32_e32 v78, v146
	v_mov_b32_e32 v79, v147
	v_mov_b32_e32 v80, v148
	v_mov_b32_e32 v81, v149
	v_pk_mul_f32 v[60:61], v[110:111], v[72:73] op_sel_hi:[1,0]
	v_lshl_add_u64 v[6:7], v[54:55], 0, v[40:41]
	v_pk_fma_f32 v[2:3], v[60:61], v[2:3], v[78:79]
	v_pk_fma_f32 v[4:5], v[66:67], v[4:5], v[80:81]
	global_store_dwordx4 v[56:57], v[2:5], off offset:3072 nt
	v_mov_b32_e32 v78, v154
	v_mov_b32_e32 v79, v155
	v_mov_b32_e32 v80, v156
	v_mov_b32_e32 v81, v157
	v_mov_b32_e32 v82, v158
	v_mov_b32_e32 v83, v159
	v_mov_b32_e32 v84, v160
	v_mov_b32_e32 v85, v161
	v_lshl_add_u64 v[66:67], v[54:55], 0, v[42:43]
	v_lshl_add_u64 v[60:61], v[52:53], 0, v[42:43]
	v_add_f32_e32 v6, 1.0, v78
	v_add_f32_e32 v7, 1.0, v79
	v_add_f32_e32 v9, 1.0, v80
	v_add_f32_e32 v56, 1.0, v81
	v_fma_f32 v2, v2, v6, v82
	v_fma_f32 v3, v3, v7, v83
	v_fma_f32 v4, v4, v9, v84
	v_fmac_f32_e32 v85, v5, v56
	v_cvt_pk_bf16_f32 v2, v2, v3
	v_cvt_pk_bf16_f32 v3, v4, v85
	global_store_dwordx2 v[0:1], v[2:3], off offset:1536
	v_mov_b32_e32 v2, v162
	v_mov_b32_e32 v3, v163
	v_mov_b32_e32 v4, v164
	v_mov_b32_e32 v5, v165
	v_mov_b32_e32 v56, v166
	v_mov_b32_e32 v57, v167
	v_mov_b32_e32 v58, v168
; __device__ __forceinline__ unsigned cvt_pk_bf16(float lo, float hi) { unsigned r; asm volatile("v_cvt_pk_bf16_f32 %0, %1, %2" : "=v"(r) : "v"(lo), "v"(hi)); return r; }
; __device__ __forceinline__ void phase_ln(const Params& p, int s) {
;     ...
;         for (int i = 0; i < 8; ++i) { const int c = i * 256 + lane * 4; const f32x4 g4 = *(const f32x4*)(lg + c), b4 = *(const f32x4*)(lb + c); f32x4 xn;
; #pragma unroll
;             for (int j = 0; j < 4; ++j) xn[j] = (v[i][j] - mean) * rs * g4[j] + b4[j];
;             __builtin_nontemporal_store(xn, (f32x4*)(p.out + (size_t)row * 2048 + c));
;             if (s < 3) { const float* mn = mods + (size_t)(s + 1) * 24576 + b * 6144; const f32x4 sh = *(const f32x4*)(mn + c), scl = *(const f32x4*)(mn + 2048 + c);
;                 u32x2 o; o[0] = cvt_pk_bf16(xn[0] * (1.f + scl[0]) + sh[0], xn[1] * (1.f + scl[1]) + sh[1]); o[1] = cvt_pk_bf16(xn[2] * (1.f + scl[2]) + sh[2], xn[3] * (1.f + scl[3]) + sh[3]);
;                 *(u32x2*)(H + (size_t)row * 2048 + c) = o; } }
	v_mov_b32_e32 v59, v169
	v_pk_mul_f32 v[78:79], v[114:115], v[72:73] op_sel_hi:[1,0]
	v_pk_mul_f32 v[80:81], v[116:117], v[72:73] op_sel_hi:[1,0]
	v_lshl_add_u64 v[6:7], v[50:51], 0, v[42:43]
	v_pk_fma_f32 v[2:3], v[78:79], v[2:3], v[56:57]
	v_pk_fma_f32 v[4:5], v[80:81], v[4:5], v[58:59]
	global_store_dwordx4 v[6:7], v[2:5], off nt
	v_mov_b32_e32 v56, v172
	v_mov_b32_e32 v57, v173
	v_mov_b32_e32 v58, v174
	v_mov_b32_e32 v59, v175
	v_mov_b32_e32 v78, v176
	v_mov_b32_e32 v79, v177
	v_mov_b32_e32 v80, v178
	v_mov_b32_e32 v81, v179
	v_lshl_add_u64 v[66:67], v[54:55], 0, v[44:45]
	v_lshl_add_u64 v[60:61], v[52:53], 0, v[44:45]
	v_add_f32_e32 v6, 1.0, v56
	v_add_f32_e32 v7, 1.0, v57
	v_add_f32_e32 v9, 1.0, v58
	v_add_f32_e32 v56, 1.0, v59
	v_fma_f32 v2, v2, v6, v78
	v_fma_f32 v3, v3, v7, v79
	v_fma_f32 v4, v4, v9, v80
	v_fmac_f32_e32 v81, v5, v56
	v_cvt_pk_bf16_f32 v2, v2, v3
	v_cvt_pk_bf16_f32 v3, v4, v81
	global_store_dwordx2 v[0:1], v[2:3], off offset:2048
	v_mov_b32_e32 v2, v180
	v_mov_b32_e32 v3, v181
	v_mov_b32_e32 v4, v182
	v_mov_b32_e32 v5, v183
	v_mov_b32_e32 v56, v184
	v_mov_b32_e32 v57, v185
	v_mov_b32_e32 v58, v186
	v_mov_b32_e32 v59, v187
	v_lshl_add_u64 v[6:7], v[50:51], 0, v[44:45]
	v_pk_fma_f32 v[2:3], v[74:75], v[2:3], v[56:57]
	v_pk_fma_f32 v[4:5], v[76:77], v[4:5], v[58:59]
	global_store_dwordx4 v[6:7], v[2:5], off nt
	v_mov_b32_e32 v56, v188
	v_mov_b32_e32 v57, v189
	v_mov_b32_e32 v58, v190
	v_mov_b32_e32 v59, v191
	v_mov_b32_e32 v74, v192
	v_mov_b32_e32 v75, v193
	v_mov_b32_e32 v76, v194
	v_mov_b32_e32 v77, v195
	v_pk_mul_f32 v[66:67], v[68:69], v[72:73] op_sel_hi:[1,0]
	v_pk_mul_f32 v[68:69], v[70:71], v[72:73] op_sel_hi:[1,0]
	v_lshl_add_u64 v[60:61], v[52:53], 0, v[46:47]
	v_add_f32_e32 v6, 1.0, v56
	v_add_f32_e32 v7, 1.0, v57
	v_add_f32_e32 v9, 1.0, v58
	v_add_f32_e32 v56, 1.0, v59
	v_fma_f32 v2, v2, v6, v74
	v_fma_f32 v3, v3, v7, v75
	v_fma_f32 v4, v4, v9, v76
	v_fmac_f32_e32 v77, v5, v56
	v_cvt_pk_bf16_f32 v2, v2, v3
	v_cvt_pk_bf16_f32 v3, v4, v77
	global_store_dwordx2 v[0:1], v[2:3], off offset:2560
	v_mov_b32_e32 v2, v196
	v_mov_b32_e32 v3, v197
	v_mov_b32_e32 v4, v198
	v_mov_b32_e32 v5, v199
	v_mov_b32_e32 v56, v200
	v_mov_b32_e32 v57, v201
	v_mov_b32_e32 v58, v202
	v_mov_b32_e32 v59, v203
	v_lshl_add_u64 v[6:7], v[50:51], 0, v[46:47]
	v_lshl_add_u64 v[74:75], v[54:55], 0, v[46:47]
	v_pk_fma_f32 v[2:3], v[66:67], v[2:3], v[56:57]
	v_pk_fma_f32 v[4:5], v[68:69], v[4:5], v[58:59]
	global_store_dwordx4 v[6:7], v[2:5], off nt
	v_mov_b32_e32 v56, v204
	v_mov_b32_e32 v57, v205
	v_mov_b32_e32 v58, v206
	v_mov_b32_e32 v59, v207
	v_mov_b32_e32 v66, v208
	v_mov_b32_e32 v67, v209
	v_mov_b32_e32 v68, v210
	v_mov_b32_e32 v69, v211
	v_lshl_add_u64 v[60:61], v[52:53], 0, v[48:49]
	v_pk_mul_f32 v[52:53], v[64:65], v[72:73] op_sel_hi:[1,0]
	v_add_f32_e32 v6, 1.0, v56
	v_add_f32_e32 v7, 1.0, v57
	v_add_f32_e32 v9, 1.0, v58
	v_add_f32_e32 v56, 1.0, v59
	v_fma_f32 v2, v2, v6, v66
	v_fma_f32 v3, v3, v7, v67
	v_fma_f32 v4, v4, v9, v68
	v_fmac_f32_e32 v69, v5, v56
	v_cvt_pk_bf16_f32 v2, v2, v3
	v_cvt_pk_bf16_f32 v3, v4, v69
	global_store_dwordx2 v[0:1], v[2:3], off offset:3072
	v_mov_b32_e32 v2, v212
	v_mov_b32_e32 v3, v213
	v_mov_b32_e32 v4, v214
	v_mov_b32_e32 v5, v215
	v_mov_b32_e32 v56, v216
	v_mov_b32_e32 v57, v217
	v_mov_b32_e32 v58, v218
	v_mov_b32_e32 v59, v219
	v_lshl_add_u64 v[6:7], v[50:51], 0, v[48:49]
	v_pk_mul_f32 v[50:51], v[62:63], v[72:73] op_sel_hi:[1,0]
	v_lshl_add_u64 v[66:67], v[54:55], 0, v[48:49]
	v_pk_fma_f32 v[2:3], v[50:51], v[2:3], v[56:57]
	v_pk_fma_f32 v[4:5], v[52:53], v[4:5], v[58:59]
	global_store_dwordx4 v[6:7], v[2:5], off nt
	v_mov_b32_e32 v50, v220
	v_mov_b32_e32 v51, v221
	v_mov_b32_e32 v52, v222
	v_mov_b32_e32 v53, v223
	v_mov_b32_e32 v54, v224
	v_mov_b32_e32 v55, v225
	v_mov_b32_e32 v56, v226
	v_mov_b32_e32 v57, v227
	v_add_f32_e32 v6, 1.0, v50
	v_add_f32_e32 v7, 1.0, v51
	v_add_f32_e32 v9, 1.0, v52
	v_add_f32_e32 v50, 1.0, v53
	v_fma_f32 v2, v2, v6, v54
	v_fma_f32 v3, v3, v7, v55
	v_fma_f32 v4, v4, v9, v56
	v_fmac_f32_e32 v57, v5, v50
	v_cvt_pk_bf16_f32 v2, v2, v3
	v_cvt_pk_bf16_f32 v3, v4, v57
	global_store_dwordx2 v[0:1], v[2:3], off offset:3584
	s_andn2_b64 exec, exec, s[6:7]
	s_cbranch_execnz .LBB0_1709

; __device__ __forceinline__ void phase_ln(const Params& p, int s) {
;     ...
;     for (int row = blockIdx.x * 8 + wid; row < 16384; row += gridDim.x * 8) {
;         const int b = row >> 12; const float* gate = mods + (size_t)s * 24576 + b * 6144 + 4096;
;         f32x4 v[8]; float sum = 0.f;
; #pragma unroll
;         for (int i = 0; i < 8; ++i) { const int c = i * 256 + lane * 4;
;             const f32x4 xv = __builtin_nontemporal_load((const f32x4*)(xin + (size_t)row * 2048 + c)), gt = *(const f32x4*)(gate + c); const f16x4 yv = __builtin_nontemporal_load((const f16x4*)(Y + (size_t)row * 2048 + c));
; #pragma unroll
;             for (int j = 0; j < 4; ++j) { v[i][j] = ALPHA_C * xv[j] + (1.0f + gt[j]) * (float)yv[j]; sum += v[i][j]; } }
.LBB0_1896:
	v_ashrrev_i32_e32 v8, 12, v12
	v_ashrrev_i32_e32 v13, 31, v12
	v_mul_i32_i24_e32 v8, 0x1800, v8
	v_lshlrev_b64 v[10:11], 13, v[12:13]
	v_lshlrev_b64 v[82:83], 12, v[12:13]
	v_ashrrev_i32_e32 v9, 31, v8
	v_lshl_add_u64 v[10:11], s[80:81], 0, v[10:11]
	v_lshl_add_u64 v[124:125], v[48:49], 0, v[82:83]
	v_lshlrev_b64 v[68:69], 2, v[8:9]
	v_mov_b32_e32 v59, v15
	v_mov_b32_e32 v61, v15
	v_mov_b32_e32 v63, v15
	v_mov_b32_e32 v65, v15
	global_load_dwordx4 v[0:3], v[16:17], off
	global_load_dwordx4 v[4:7], v[18:19], off
	v_lshl_add_u64 v[78:79], v[10:11], 0, v[14:15]
	global_load_dwordx2 v[148:149], v[124:125], off offset:2560 nt
	global_load_dwordx2 v[150:151], v[124:125], off offset:3072 nt
	global_load_dwordx2 v[154:155], v[124:125], off offset:3584 nt
	global_load_dwordx2 v[156:157], v[124:125], off offset:512 nt
	global_load_dwordx2 v[158:159], v[124:125], off offset:1024 nt
	global_load_dwordx2 v[160:161], v[124:125], off offset:1536 nt
	global_load_dwordx2 v[162:163], v[124:125], off offset:2048 nt
	v_lshl_add_u64 v[70:71], s[82:83], 0, v[68:69]
	v_mov_b32_e32 v53, v15
	v_mov_b32_e32 v55, v15
	v_mov_b32_e32 v57, v15
	v_lshl_add_u64 v[76:77], v[10:11], 0, v[58:59]
	v_lshl_add_u64 v[74:75], v[10:11], 0, v[60:61]
	v_lshl_add_u64 v[72:73], v[10:11], 0, v[62:63]
	v_lshl_add_u64 v[66:67], v[10:11], 0, v[64:65]
	global_load_dwordx4 v[8:11], v[78:79], off nt
	global_load_dwordx4 v[86:89], v[78:79], off offset:1024 nt
	global_load_dwordx4 v[92:95], v[78:79], off offset:2048 nt
	global_load_dwordx4 v[96:99], v[78:79], off offset:3072 nt
	global_load_dwordx4 v[100:103], v[76:77], off nt
	global_load_dwordx4 v[104:107], v[74:75], off nt
	global_load_dwordx4 v[108:111], v[72:73], off nt
	global_load_dwordx4 v[112:115], v[66:67], off nt
	v_lshl_add_u64 v[84:85], v[70:71], 0, s[14:15]
	v_lshl_add_u64 v[120:121], v[84:85], 0, v[14:15]
	v_lshl_add_u64 v[128:129], v[84:85], 0, v[52:53]
	v_lshl_add_u64 v[132:133], v[84:85], 0, v[54:55]
	v_lshl_add_u64 v[136:137], v[84:85], 0, v[56:57]
	v_lshl_add_u64 v[140:141], v[84:85], 0, v[58:59]
	v_lshl_add_u64 v[144:145], v[84:85], 0, v[60:61]
	v_lshl_add_u64 v[126:127], v[84:85], 0, v[62:63]
	v_lshl_add_u64 v[116:117], v[84:85], 0, v[64:65]
	global_load_dwordx4 v[116:119], v[116:117], off
	s_nop 0
	global_load_dwordx4 v[120:123], v[120:121], off
	s_nop 0
	global_load_dwordx2 v[164:165], v[124:125], off nt
	s_nop 0
	global_load_dwordx4 v[124:127], v[126:127], off
	s_nop 0
	global_load_dwordx4 v[128:131], v[128:129], off
	s_nop 0
	global_load_dwordx4 v[132:135], v[132:133], off
	s_nop 0
	global_load_dwordx4 v[136:139], v[136:137], off
	s_nop 0
	global_load_dwordx4 v[140:143], v[140:141], off
	s_nop 0
	global_load_dwordx4 v[144:147], v[144:145], off
	v_lshl_add_u64 v[68:69], s[6:7], 0, v[68:69]
	v_lshl_add_u64 v[70:71], v[68:69], 0, s[4:5]
	v_lshl_add_u64 v[84:85], v[70:71], 0, v[14:15]
	v_lshl_add_u64 v[80:81], v[68:69], 0, v[14:15]
	v_add_u32_e32 v12, s2, v12
	s_waitcnt vmcnt(23)
	v_cvt_f32_f16_e32 v180, v148
	s_waitcnt vmcnt(22)
	v_cvt_f32_f16_e32 v182, v150
	s_waitcnt vmcnt(21)
	v_cvt_f32_f16_e32 v168, v154
	v_cvt_f32_f16_sdwa v169, v154 dst_sel:DWORD dst_unused:UNUSED_PAD src0_sel:WORD_1
	v_cvt_f32_f16_e32 v166, v155
	v_cvt_f32_f16_sdwa v167, v155 dst_sel:DWORD dst_unused:UNUSED_PAD src0_sel:WORD_1
	v_cvt_f32_f16_e32 v154, v151
	v_cvt_f32_f16_sdwa v155, v151 dst_sel:DWORD dst_unused:UNUSED_PAD src0_sel:WORD_1
	v_cvt_f32_f16_sdwa v183, v150 dst_sel:DWORD dst_unused:UNUSED_PAD src0_sel:WORD_1
	s_waitcnt vmcnt(20)
	v_cvt_f32_f16_e32 v172, v156
	v_cvt_f32_f16_sdwa v173, v156 dst_sel:DWORD dst_unused:UNUSED_PAD src0_sel:WORD_1
	v_cvt_f32_f16_e32 v156, v157
	v_cvt_f32_f16_sdwa v157, v157 dst_sel:DWORD dst_unused:UNUSED_PAD src0_sel:WORD_1
	s_waitcnt vmcnt(19)
	v_cvt_f32_f16_e32 v174, v158
	v_cvt_f32_f16_sdwa v175, v158 dst_sel:DWORD dst_unused:UNUSED_PAD src0_sel:WORD_1
	v_cvt_f32_f16_e32 v158, v159
	v_cvt_f32_f16_sdwa v159, v159 dst_sel:DWORD dst_unused:UNUSED_PAD src0_sel:WORD_1
	s_waitcnt vmcnt(8)
	v_pk_add_f32 v[116:117], v[116:117], 1.0 op_sel_hi:[1,0]
	s_waitcnt vmcnt(7)
	v_pk_add_f32 v[120:121], v[120:121], 1.0 op_sel_hi:[1,0]
	s_waitcnt vmcnt(6)
	v_cvt_f32_f16_e32 v150, v164
	v_cvt_f32_f16_sdwa v151, v164 dst_sel:DWORD dst_unused:UNUSED_PAD src0_sel:WORD_1
	v_cvt_f32_f16_e32 v164, v165
	v_cvt_f32_f16_sdwa v165, v165 dst_sel:DWORD dst_unused:UNUSED_PAD src0_sel:WORD_1
	v_pk_mul_f32 v[116:117], v[116:117], v[168:169]
	v_pk_add_f32 v[118:119], v[118:119], 1.0 op_sel_hi:[1,0]
	v_pk_fma_f32 v[112:113], v[112:113], s[16:17], v[116:117] op_sel_hi:[1,0,1]
	v_pk_mul_f32 v[116:117], v[120:121], v[150:151]
	v_pk_add_f32 v[122:123], v[122:123], 1.0 op_sel_hi:[1,0]
	v_pk_mul_f32 v[118:119], v[118:119], v[166:167]
	v_pk_fma_f32 v[8:9], v[8:9], s[16:17], v[116:117] op_sel_hi:[1,0,1]
	v_pk_fma_f32 v[114:115], v[114:115], s[16:17], v[118:119] op_sel_hi:[1,0,1]
	v_pk_mul_f32 v[118:119], v[122:123], v[164:165]
	v_add_f32_e32 v13, 0, v8
	s_waitcnt vmcnt(4)
	v_pk_add_f32 v[128:129], v[128:129], 1.0 op_sel_hi:[1,0]
	v_pk_fma_f32 v[10:11], v[10:11], s[16:17], v[118:119] op_sel_hi:[1,0,1]
	v_add_f32_e32 v13, v9, v13
	v_pk_mul_f32 v[128:129], v[128:129], v[172:173]
	v_add_f32_e32 v13, v10, v13
	v_pk_add_f32 v[130:131], v[130:131], 1.0 op_sel_hi:[1,0]
	v_pk_fma_f32 v[86:87], v[86:87], s[16:17], v[128:129] op_sel_hi:[1,0,1]
	v_add_f32_e32 v13, v11, v13
	v_pk_mul_f32 v[130:131], v[130:131], v[156:157]
	v_add_f32_e32 v13, v86, v13
	s_waitcnt vmcnt(3)
; __device__ __forceinline__ void phase_ln(const Params& p, int s) {
;     ...
;             for (int j = 0; j < 4; ++j) { v[i][j] = ALPHA_C * xv[j] + (1.0f + gt[j]) * (float)yv[j]; sum += v[i][j]; } }
;         sum = wave_sum(sum); const float mean = sum * (1.0f / 2048.0f); float sq = 0.f;
; #pragma unroll
;         for (int i = 0; i < 8; ++i)
; #pragma unroll
;             for (int j = 0; j < 4; ++j) { const float d = v[i][j] - mean; sq += d * d; }
;         sq = wave_sum(sq); const float rs = rsqrtf(sq * (1.0f / 2048.0f) + 1e-5f);
	v_pk_add_f32 v[132:133], v[132:133], 1.0 op_sel_hi:[1,0]
	v_pk_fma_f32 v[88:89], v[88:89], s[16:17], v[130:131] op_sel_hi:[1,0,1]
	v_add_f32_e32 v13, v87, v13
	v_cvt_f32_f16_e32 v176, v160
	v_cvt_f32_f16_sdwa v177, v160 dst_sel:DWORD dst_unused:UNUSED_PAD src0_sel:WORD_1
	v_pk_mul_f32 v[132:133], v[132:133], v[174:175]
	v_add_f32_e32 v13, v88, v13
	v_pk_add_f32 v[134:135], v[134:135], 1.0 op_sel_hi:[1,0]
	v_pk_fma_f32 v[92:93], v[92:93], s[16:17], v[132:133] op_sel_hi:[1,0,1]
	v_add_f32_e32 v13, v89, v13
	v_cvt_f32_f16_e32 v160, v161
	v_cvt_f32_f16_sdwa v161, v161 dst_sel:DWORD dst_unused:UNUSED_PAD src0_sel:WORD_1
	v_pk_mul_f32 v[134:135], v[134:135], v[158:159]
	v_add_f32_e32 v13, v92, v13
	s_waitcnt vmcnt(2)
	v_pk_add_f32 v[136:137], v[136:137], 1.0 op_sel_hi:[1,0]
	v_pk_fma_f32 v[94:95], v[94:95], s[16:17], v[134:135] op_sel_hi:[1,0,1]
	v_add_f32_e32 v13, v93, v13
	v_cvt_f32_f16_e32 v178, v162
	v_cvt_f32_f16_sdwa v179, v162 dst_sel:DWORD dst_unused:UNUSED_PAD src0_sel:WORD_1
	v_pk_mul_f32 v[136:137], v[136:137], v[176:177]
	v_add_f32_e32 v13, v94, v13
	v_pk_add_f32 v[138:139], v[138:139], 1.0 op_sel_hi:[1,0]
	v_pk_fma_f32 v[96:97], v[96:97], s[16:17], v[136:137] op_sel_hi:[1,0,1]
	v_add_f32_e32 v13, v95, v13
	v_cvt_f32_f16_e32 v162, v163
	v_cvt_f32_f16_sdwa v163, v163 dst_sel:DWORD dst_unused:UNUSED_PAD src0_sel:WORD_1
	v_pk_mul_f32 v[138:139], v[138:139], v[160:161]
	v_add_f32_e32 v13, v96, v13
	s_waitcnt vmcnt(1)
	v_pk_add_f32 v[140:141], v[140:141], 1.0 op_sel_hi:[1,0]
	v_pk_fma_f32 v[98:99], v[98:99], s[16:17], v[138:139] op_sel_hi:[1,0,1]
	v_add_f32_e32 v13, v97, v13
	v_cvt_f32_f16_sdwa v181, v148 dst_sel:DWORD dst_unused:UNUSED_PAD src0_sel:WORD_1
	v_pk_mul_f32 v[140:141], v[140:141], v[178:179]
	v_add_f32_e32 v13, v98, v13
	v_pk_add_f32 v[142:143], v[142:143], 1.0 op_sel_hi:[1,0]
	v_pk_fma_f32 v[100:101], v[100:101], s[16:17], v[140:141] op_sel_hi:[1,0,1]
	v_add_f32_e32 v13, v99, v13
	v_cvt_f32_f16_e32 v148, v149
	v_cvt_f32_f16_sdwa v149, v149 dst_sel:DWORD dst_unused:UNUSED_PAD src0_sel:WORD_1
	v_pk_mul_f32 v[142:143], v[142:143], v[162:163]
	v_add_f32_e32 v13, v100, v13
	s_waitcnt vmcnt(0)
	v_pk_add_f32 v[144:145], v[144:145], 1.0 op_sel_hi:[1,0]
	v_pk_fma_f32 v[102:103], v[102:103], s[16:17], v[142:143] op_sel_hi:[1,0,1]
	v_add_f32_e32 v13, v101, v13
	v_pk_mul_f32 v[144:145], v[144:145], v[180:181]
	v_add_f32_e32 v13, v102, v13
	v_pk_add_f32 v[146:147], v[146:147], 1.0 op_sel_hi:[1,0]
	v_pk_fma_f32 v[104:105], v[104:105], s[16:17], v[144:145] op_sel_hi:[1,0,1]
	v_add_f32_e32 v13, v103, v13
	v_pk_mul_f32 v[146:147], v[146:147], v[148:149]
	v_add_f32_e32 v13, v104, v13
	v_pk_add_f32 v[124:125], v[124:125], 1.0 op_sel_hi:[1,0]
	v_pk_fma_f32 v[106:107], v[106:107], s[16:17], v[146:147] op_sel_hi:[1,0,1]
	v_add_f32_e32 v13, v105, v13
	v_pk_mul_f32 v[124:125], v[124:125], v[182:183]
	v_add_f32_e32 v13, v106, v13
	v_pk_add_f32 v[126:127], v[126:127], 1.0 op_sel_hi:[1,0]
	v_pk_fma_f32 v[108:109], v[108:109], s[16:17], v[124:125] op_sel_hi:[1,0,1]
	v_add_f32_e32 v13, v107, v13
	v_pk_mul_f32 v[126:127], v[126:127], v[154:155]
	v_add_f32_e32 v13, v108, v13
	v_pk_fma_f32 v[110:111], v[110:111], s[16:17], v[126:127] op_sel_hi:[1,0,1]
	v_add_f32_e32 v13, v109, v13
	v_add_f32_e32 v13, v110, v13
	v_add_f32_e32 v13, v111, v13
	v_add_f32_e32 v13, v112, v13
	v_add_f32_e32 v13, v113, v13
	v_add_f32_e32 v13, v114, v13
	v_add_f32_e32 v13, v115, v13
	s_nop 1
	v_add_f32_dpp v13, v13, v13 quad_perm:[1,0,3,2] row_mask:0xf bank_mask:0xf bound_ctrl:1
	s_nop 1
	v_add_f32_dpp v13, v13, v13 quad_perm:[2,3,0,1] row_mask:0xf bank_mask:0xf bound_ctrl:1
	s_nop 1
	v_add_f32_dpp v13, v13, v13 row_half_mirror row_mask:0xf bank_mask:0xf bound_ctrl:1
	s_nop 1
	v_add_f32_dpp v13, v13, v13 row_mirror row_mask:0xf bank_mask:0xf bound_ctrl:1
	s_nop 0
	v_readlane_b32 s26, v13, 16
	v_readlane_b32 s27, v13, 48
	v_readlane_b32 s20, v13, 0
	v_readlane_b32 s21, v13, 32
	v_mov_b32_e32 v116, s26
	v_mov_b32_e32 v117, s27
	v_pk_add_f32 v[116:117], s[20:21], v[116:117]
	s_nop 0
	v_add_f32_e32 v13, v116, v117
	v_mul_f32_e32 v90, 0x3a000000, v13
	v_pk_add_f32 v[116:117], v[8:9], v[90:91] op_sel_hi:[1,0] neg_lo:[0,1] neg_hi:[0,1]
	v_pk_add_f32 v[118:119], v[10:11], v[90:91] op_sel_hi:[1,0] neg_lo:[0,1] neg_hi:[0,1]
	v_pk_add_f32 v[128:129], v[96:97], v[90:91] op_sel_hi:[1,0] neg_lo:[0,1] neg_hi:[0,1]
	v_pk_mul_f32 v[96:97], v[116:117], v[116:117]
	v_pk_add_f32 v[130:131], v[98:99], v[90:91] op_sel_hi:[1,0] neg_lo:[0,1] neg_hi:[0,1]
	v_pk_mul_f32 v[98:99], v[118:119], v[118:119]
	v_add_f32_e32 v13, v96, v97
	v_pk_add_f32 v[120:121], v[86:87], v[90:91] op_sel_hi:[1,0] neg_lo:[0,1] neg_hi:[0,1]
	v_add_f32_e32 v13, v98, v13
	v_pk_add_f32 v[132:133], v[100:101], v[90:91] op_sel_hi:[1,0] neg_lo:[0,1] neg_hi:[0,1]
	v_pk_mul_f32 v[100:101], v[120:121], v[120:121]
	v_add_f32_e32 v13, v99, v13
	v_pk_add_f32 v[122:123], v[88:89], v[90:91] op_sel_hi:[1,0] neg_lo:[0,1] neg_hi:[0,1]
	v_add_f32_e32 v13, v100, v13
	v_pk_add_f32 v[134:135], v[102:103], v[90:91] op_sel_hi:[1,0] neg_lo:[0,1] neg_hi:[0,1]
	v_pk_mul_f32 v[102:103], v[122:123], v[122:123]
	v_add_f32_e32 v13, v101, v13
	v_pk_add_f32 v[124:125], v[92:93], v[90:91] op_sel_hi:[1,0] neg_lo:[0,1] neg_hi:[0,1]
	v_add_f32_e32 v13, v102, v13
	v_pk_add_f32 v[92:93], v[104:105], v[90:91] op_sel_hi:[1,0] neg_lo:[0,1] neg_hi:[0,1]
	v_pk_mul_f32 v[104:105], v[124:125], v[124:125]
	v_add_f32_e32 v13, v103, v13
	v_pk_add_f32 v[126:127], v[94:95], v[90:91] op_sel_hi:[1,0] neg_lo:[0,1] neg_hi:[0,1]
	v_add_f32_e32 v13, v104, v13
	v_pk_add_f32 v[94:95], v[106:107], v[90:91] op_sel_hi:[1,0] neg_lo:[0,1] neg_hi:[0,1]
	v_pk_mul_f32 v[106:107], v[126:127], v[126:127]
; __device__ __forceinline__ unsigned cvt_pk_bf16(float lo, float hi) { unsigned r; asm volatile("v_cvt_pk_bf16_f32 %0, %1, %2" : "=v"(r) : "v"(lo), "v"(hi)); return r; }
; __device__ __forceinline__ void phase_ln(const Params& p, int s) {
;     ...
;         sq = wave_sum(sq); const float rs = rsqrtf(sq * (1.0f / 2048.0f) + 1e-5f);
; #pragma unroll
;         for (int i = 0; i < 8; ++i) { const int c = i * 256 + lane * 4; const f32x4 g4 = *(const f32x4*)(lg + c), b4 = *(const f32x4*)(lb + c); f32x4 xn;
; #pragma unroll
;             for (int j = 0; j < 4; ++j) xn[j] = (v[i][j] - mean) * rs * g4[j] + b4[j];
;             __builtin_nontemporal_store(xn, (f32x4*)(p.out + (size_t)row * 2048 + c));
;             if (s < 3) { const float* mn = mods + (size_t)(s + 1) * 24576 + b * 6144; const f32x4 sh = *(const f32x4*)(mn + c), scl = *(const f32x4*)(mn + 2048 + c);
;                 u32x2 o; o[0] = cvt_pk_bf16(xn[0] * (1.f + scl[0]) + sh[0], xn[1] * (1.f + scl[1]) + sh[1]); o[1] = cvt_pk_bf16(xn[2] * (1.f + scl[2]) + sh[2], xn[3] * (1.f + scl[3]) + sh[3]);
;                 *(u32x2*)(H + (size_t)row * 2048 + c) = o; } }
	v_add_f32_e32 v13, v105, v13
	v_add_f32_e32 v13, v106, v13
	v_pk_add_f32 v[86:87], v[108:109], v[90:91] op_sel_hi:[1,0] neg_lo:[0,1] neg_hi:[0,1]
	v_pk_mul_f32 v[108:109], v[128:129], v[128:129]
	v_add_f32_e32 v13, v107, v13
	v_add_f32_e32 v13, v108, v13
	v_pk_add_f32 v[88:89], v[110:111], v[90:91] op_sel_hi:[1,0] neg_lo:[0,1] neg_hi:[0,1]
	v_pk_mul_f32 v[110:111], v[130:131], v[130:131]
	v_add_f32_e32 v13, v109, v13
	v_add_f32_e32 v13, v110, v13
	v_pk_add_f32 v[8:9], v[112:113], v[90:91] op_sel_hi:[1,0] neg_lo:[0,1] neg_hi:[0,1]
	v_pk_mul_f32 v[112:113], v[132:133], v[132:133]
	v_add_f32_e32 v13, v111, v13
	v_add_f32_e32 v13, v112, v13
	v_pk_add_f32 v[10:11], v[114:115], v[90:91] op_sel_hi:[1,0] neg_lo:[0,1] neg_hi:[0,1]
	v_pk_mul_f32 v[114:115], v[134:135], v[134:135]
	v_add_f32_e32 v13, v113, v13
	v_add_f32_e32 v13, v114, v13
	v_pk_mul_f32 v[136:137], v[92:93], v[92:93]
	v_add_f32_e32 v13, v115, v13
	v_add_f32_e32 v13, v136, v13
	v_pk_mul_f32 v[138:139], v[94:95], v[94:95]
	v_add_f32_e32 v13, v137, v13
	v_add_f32_e32 v13, v138, v13
	v_pk_mul_f32 v[140:141], v[86:87], v[86:87]
	v_add_f32_e32 v13, v139, v13
	v_add_f32_e32 v13, v140, v13
	v_pk_mul_f32 v[142:143], v[88:89], v[88:89]
	v_add_f32_e32 v13, v141, v13
	v_add_f32_e32 v13, v142, v13
	v_pk_mul_f32 v[144:145], v[8:9], v[8:9]
	v_add_f32_e32 v13, v143, v13
	v_add_f32_e32 v13, v144, v13
	v_pk_mul_f32 v[146:147], v[10:11], v[10:11]
	v_add_f32_e32 v13, v145, v13
	v_add_f32_e32 v13, v146, v13
	v_add_f32_e32 v13, v147, v13
	s_nop 1
	v_add_f32_dpp v13, v13, v13 quad_perm:[1,0,3,2] row_mask:0xf bank_mask:0xf bound_ctrl:1
	s_nop 1
	v_add_f32_dpp v13, v13, v13 quad_perm:[2,3,0,1] row_mask:0xf bank_mask:0xf bound_ctrl:1
	s_nop 1
	v_add_f32_dpp v13, v13, v13 row_half_mirror row_mask:0xf bank_mask:0xf bound_ctrl:1
	s_nop 1
	v_add_f32_dpp v13, v13, v13 row_mirror row_mask:0xf bank_mask:0xf bound_ctrl:1
	s_nop 0
	v_readlane_b32 s26, v13, 16
	v_readlane_b32 s27, v13, 48
	v_readlane_b32 s20, v13, 0
	v_readlane_b32 s21, v13, 32
	v_mov_b32_e32 v96, s26
	v_mov_b32_e32 v97, s27
	v_pk_add_f32 v[96:97], s[20:21], v[96:97]
	s_nop 0
	v_add_f32_e32 v13, v96, v97
	v_fmamk_f32 v13, v13, 0x3a000000, v91
	v_mul_f32_e32 v90, 0x4b800000, v13
	v_cmp_gt_f32_e32 vcc, s3, v13
	s_nop 1
	v_cndmask_b32_e32 v13, v13, v90, vcc
	v_rsq_f32_e32 v13, v13
	s_nop 0
	v_mul_f32_e32 v90, 0x45800000, v13
	v_cndmask_b32_e32 v90, v13, v90, vcc
	v_pk_mul_f32 v[96:97], v[116:117], v[90:91] op_sel_hi:[1,0]
	v_pk_mul_f32 v[98:99], v[118:119], v[90:91] op_sel_hi:[1,0]
	v_pk_fma_f32 v[4:5], v[0:1], v[96:97], v[4:5]
	v_pk_fma_f32 v[6:7], v[2:3], v[98:99], v[6:7]
	global_load_dwordx4 v[104:107], v[84:85], off
	global_load_dwordx4 v[108:111], v[80:81], off
	global_load_dwordx4 v[112:115], v[20:21], off
	global_load_dwordx4 v[116:119], v[22:23], off
	v_lshl_add_u64 v[136:137], v[70:71], 0, v[52:53]
	global_load_dwordx4 v[136:139], v[136:137], off
	global_load_dwordx4 v[140:143], v[80:81], off offset:1024
	global_load_dwordx4 v[144:147], v[24:25], off
	global_load_dwordx4 v[148:151], v[26:27], off
	v_lshl_add_u64 v[154:155], v[70:71], 0, v[54:55]
	global_load_dwordx4 v[154:157], v[154:155], off
	global_load_dwordx4 v[158:161], v[80:81], off offset:2048
	global_load_dwordx4 v[162:165], v[28:29], off
	global_load_dwordx4 v[166:169], v[30:31], off
	v_lshl_add_u64 v[172:173], v[70:71], 0, v[56:57]
	global_load_dwordx4 v[172:175], v[172:173], off
	global_load_dwordx4 v[176:179], v[80:81], off offset:3072
	global_load_dwordx4 v[180:183], v[32:33], off
	global_load_dwordx4 v[184:187], v[34:35], off
	v_lshl_add_u64 v[188:189], v[70:71], 0, v[58:59]
	global_load_dwordx4 v[188:191], v[188:189], off
	v_lshl_add_u64 v[192:193], v[68:69], 0, v[58:59]
	global_load_dwordx4 v[192:195], v[192:193], off
	global_load_dwordx4 v[196:199], v[36:37], off
	global_load_dwordx4 v[200:203], v[38:39], off
	v_lshl_add_u64 v[204:205], v[70:71], 0, v[60:61]
	global_load_dwordx4 v[204:207], v[204:205], off
	v_lshl_add_u64 v[208:209], v[68:69], 0, v[60:61]
	global_load_dwordx4 v[208:211], v[208:209], off
	global_load_dwordx4 v[212:215], v[40:41], off
	global_load_dwordx4 v[216:219], v[42:43], off
	v_lshl_add_u64 v[220:221], v[70:71], 0, v[62:63]
	global_load_dwordx4 v[220:223], v[220:221], off
	v_lshl_add_u64 v[224:225], v[68:69], 0, v[62:63]
	global_load_dwordx4 v[224:227], v[224:225], off
	global_load_dwordx4 v[228:231], v[44:45], off
	global_load_dwordx4 v[232:235], v[46:47], off
	v_lshl_add_u64 v[236:237], v[70:71], 0, v[64:65]
	global_load_dwordx4 v[236:239], v[236:237], off
	s_waitcnt vmcnt(0)
; __device__ __forceinline__ unsigned cvt_pk_bf16(float lo, float hi) { unsigned r; asm volatile("v_cvt_pk_bf16_f32 %0, %1, %2" : "=v"(r) : "v"(lo), "v"(hi)); return r; }
; __device__ __forceinline__ void phase_ln(const Params& p, int s) {
;     ...
;         for (int i = 0; i < 8; ++i) { const int c = i * 256 + lane * 4; const f32x4 g4 = *(const f32x4*)(lg + c), b4 = *(const f32x4*)(lb + c); f32x4 xn;
; #pragma unroll
;             for (int j = 0; j < 4; ++j) xn[j] = (v[i][j] - mean) * rs * g4[j] + b4[j];
;             __builtin_nontemporal_store(xn, (f32x4*)(p.out + (size_t)row * 2048 + c));
;             if (s < 3) { const float* mn = mods + (size_t)(s + 1) * 24576 + b * 6144; const f32x4 sh = *(const f32x4*)(mn + c), scl = *(const f32x4*)(mn + 2048 + c);
;                 u32x2 o; o[0] = cvt_pk_bf16(xn[0] * (1.f + scl[0]) + sh[0], xn[1] * (1.f + scl[1]) + sh[1]); o[1] = cvt_pk_bf16(xn[2] * (1.f + scl[2]) + sh[2], xn[3] * (1.f + scl[3]) + sh[3]);
;                 *(u32x2*)(H + (size_t)row * 2048 + c) = o; } }
	global_store_dwordx4 v[78:79], v[4:7], off nt
	v_mov_b32_e32 v96, v104
	v_mov_b32_e32 v97, v105
	v_mov_b32_e32 v98, v106
	v_mov_b32_e32 v99, v107
	v_mov_b32_e32 v100, v108
	v_mov_b32_e32 v101, v109
	v_mov_b32_e32 v102, v110
	v_mov_b32_e32 v103, v111
	v_lshl_add_u64 v[0:1], v[50:51], 0, v[82:83]
	v_cmp_lt_i32_e32 vcc, s17, v12
	s_or_b64 s[12:13], vcc, s[12:13]
	v_add_f32_e32 v2, 1.0, v96
	v_add_f32_e32 v3, 1.0, v97
	v_add_f32_e32 v13, 1.0, v98
	v_add_f32_e32 v82, 1.0, v99
	v_fma_f32 v2, v2, v4, v100
	v_fma_f32 v3, v3, v5, v101
	v_fma_f32 v4, v13, v6, v102
	v_fmac_f32_e32 v103, v82, v7
	v_cvt_pk_bf16_f32 v2, v2, v3
	v_cvt_pk_bf16_f32 v3, v4, v103
	global_store_dwordx2 v[0:1], v[2:3], off
	v_mov_b32_e32 v2, v112
	v_mov_b32_e32 v3, v113
	v_mov_b32_e32 v4, v114
	v_mov_b32_e32 v5, v115
	v_mov_b32_e32 v82, v116
	v_mov_b32_e32 v83, v117
	v_mov_b32_e32 v84, v118
	v_mov_b32_e32 v85, v119
	v_pk_mul_f32 v[96:97], v[120:121], v[90:91] op_sel_hi:[1,0]
	v_pk_mul_f32 v[98:99], v[122:123], v[90:91] op_sel_hi:[1,0]
	v_lshl_add_u64 v[6:7], v[70:71], 0, v[52:53]
	v_pk_fma_f32 v[2:3], v[2:3], v[96:97], v[82:83]
	v_pk_fma_f32 v[4:5], v[4:5], v[98:99], v[84:85]
	global_store_dwordx4 v[78:79], v[2:5], off offset:1024 nt
	v_mov_b32_e32 v82, v136
	v_mov_b32_e32 v83, v137
	v_mov_b32_e32 v84, v138
	v_mov_b32_e32 v85, v139
	v_mov_b32_e32 v96, v140
	v_mov_b32_e32 v97, v141
	v_mov_b32_e32 v98, v142
	v_mov_b32_e32 v99, v143
	v_add_f32_e32 v6, 1.0, v82
	v_add_f32_e32 v7, 1.0, v83
	v_add_f32_e32 v13, 1.0, v84
	v_add_f32_e32 v53, 1.0, v85
	v_fma_f32 v2, v2, v6, v96
	v_fma_f32 v3, v3, v7, v97
	v_fma_f32 v4, v4, v13, v98
	v_fmac_f32_e32 v99, v5, v53
	v_cvt_pk_bf16_f32 v2, v2, v3
	v_cvt_pk_bf16_f32 v3, v4, v99
	global_store_dwordx2 v[0:1], v[2:3], off offset:512
	v_mov_b32_e32 v2, v144
	v_mov_b32_e32 v3, v145
	v_mov_b32_e32 v4, v146
	v_mov_b32_e32 v5, v147
	v_mov_b32_e32 v82, v148
	v_mov_b32_e32 v83, v149
	v_mov_b32_e32 v84, v150
	v_mov_b32_e32 v85, v151
	v_pk_mul_f32 v[96:97], v[124:125], v[90:91] op_sel_hi:[1,0]
	v_pk_mul_f32 v[98:99], v[126:127], v[90:91] op_sel_hi:[1,0]
	v_lshl_add_u64 v[6:7], v[70:71], 0, v[54:55]
	v_pk_fma_f32 v[2:3], v[96:97], v[2:3], v[82:83]
	v_pk_fma_f32 v[4:5], v[98:99], v[4:5], v[84:85]
	global_store_dwordx4 v[78:79], v[2:5], off offset:2048 nt
	v_mov_b32_e32 v82, v154
	v_mov_b32_e32 v83, v155
	v_mov_b32_e32 v84, v156
	v_mov_b32_e32 v85, v157
	v_mov_b32_e32 v96, v158
	v_mov_b32_e32 v97, v159
	v_mov_b32_e32 v98, v160
	v_mov_b32_e32 v99, v161
	v_add_f32_e32 v6, 1.0, v82
	v_add_f32_e32 v7, 1.0, v83
	v_add_f32_e32 v13, 1.0, v84
	v_add_f32_e32 v53, 1.0, v85
	v_fma_f32 v2, v2, v6, v96
	v_fma_f32 v3, v3, v7, v97
	v_fma_f32 v4, v4, v13, v98
	v_fmac_f32_e32 v99, v5, v53
	v_cvt_pk_bf16_f32 v2, v2, v3
	v_cvt_pk_bf16_f32 v3, v4, v99
	global_store_dwordx2 v[0:1], v[2:3], off offset:1024
	v_mov_b32_e32 v2, v162
	v_mov_b32_e32 v3, v163
	v_mov_b32_e32 v4, v164
	v_mov_b32_e32 v5, v165
	v_mov_b32_e32 v82, v166
	v_mov_b32_e32 v83, v167
	v_mov_b32_e32 v84, v168
	v_mov_b32_e32 v85, v169
	v_pk_mul_f32 v[96:97], v[128:129], v[90:91] op_sel_hi:[1,0]
	v_pk_mul_f32 v[98:99], v[130:131], v[90:91] op_sel_hi:[1,0]
	v_lshl_add_u64 v[6:7], v[70:71], 0, v[56:57]
	v_pk_fma_f32 v[2:3], v[96:97], v[2:3], v[82:83]
	v_pk_fma_f32 v[4:5], v[98:99], v[4:5], v[84:85]
	global_store_dwordx4 v[78:79], v[2:5], off offset:3072 nt
	v_mov_b32_e32 v82, v172
	v_mov_b32_e32 v83, v173
	v_mov_b32_e32 v84, v174
	v_mov_b32_e32 v85, v175
	v_mov_b32_e32 v96, v176
	v_mov_b32_e32 v97, v177
	v_mov_b32_e32 v98, v178
	v_mov_b32_e32 v99, v179
	v_add_f32_e32 v6, 1.0, v82
	v_add_f32_e32 v7, 1.0, v83
	v_add_f32_e32 v13, 1.0, v84
	v_add_f32_e32 v53, 1.0, v85
	v_fma_f32 v2, v2, v6, v96
	v_fma_f32 v3, v3, v7, v97
	v_fma_f32 v4, v4, v13, v98
	v_fmac_f32_e32 v99, v5, v53
	v_cvt_pk_bf16_f32 v2, v2, v3
	v_cvt_pk_bf16_f32 v3, v4, v99
	global_store_dwordx2 v[0:1], v[2:3], off offset:1536
	v_mov_b32_e32 v2, v180
	v_mov_b32_e32 v3, v181
	v_mov_b32_e32 v4, v182
	v_mov_b32_e32 v5, v183
	v_mov_b32_e32 v78, v184
	v_mov_b32_e32 v79, v185
	v_mov_b32_e32 v80, v186
	v_mov_b32_e32 v81, v187
	v_pk_mul_f32 v[82:83], v[132:133], v[90:91] op_sel_hi:[1,0]
; __device__ __forceinline__ unsigned cvt_pk_bf16(float lo, float hi) { unsigned r; asm volatile("v_cvt_pk_bf16_f32 %0, %1, %2" : "=v"(r) : "v"(lo), "v"(hi)); return r; }
; __device__ __forceinline__ void phase_ln(const Params& p, int s) {
;     ...
;         for (int i = 0; i < 8; ++i) { const int c = i * 256 + lane * 4; const f32x4 g4 = *(const f32x4*)(lg + c), b4 = *(const f32x4*)(lb + c); f32x4 xn;
; #pragma unroll
;             for (int j = 0; j < 4; ++j) xn[j] = (v[i][j] - mean) * rs * g4[j] + b4[j];
;             __builtin_nontemporal_store(xn, (f32x4*)(p.out + (size_t)row * 2048 + c));
;             if (s < 3) { const float* mn = mods + (size_t)(s + 1) * 24576 + b * 6144; const f32x4 sh = *(const f32x4*)(mn + c), scl = *(const f32x4*)(mn + 2048 + c);
;                 u32x2 o; o[0] = cvt_pk_bf16(xn[0] * (1.f + scl[0]) + sh[0], xn[1] * (1.f + scl[1]) + sh[1]); o[1] = cvt_pk_bf16(xn[2] * (1.f + scl[2]) + sh[2], xn[3] * (1.f + scl[3]) + sh[3]);
;                 *(u32x2*)(H + (size_t)row * 2048 + c) = o; } }
	v_pk_mul_f32 v[96:97], v[134:135], v[90:91] op_sel_hi:[1,0]
	v_lshl_add_u64 v[84:85], v[70:71], 0, v[58:59]
	v_lshl_add_u64 v[6:7], v[68:69], 0, v[58:59]
	v_pk_fma_f32 v[2:3], v[82:83], v[2:3], v[78:79]
	v_pk_fma_f32 v[4:5], v[96:97], v[4:5], v[80:81]
	global_store_dwordx4 v[76:77], v[2:5], off nt
	v_mov_b32_e32 v76, v188
	v_mov_b32_e32 v77, v189
	v_mov_b32_e32 v78, v190
	v_mov_b32_e32 v79, v191
	v_mov_b32_e32 v80, v192
	v_mov_b32_e32 v81, v193
	v_mov_b32_e32 v82, v194
	v_mov_b32_e32 v83, v195
	v_pk_mul_f32 v[84:85], v[94:95], v[90:91] op_sel_hi:[1,0]
	v_add_f32_e32 v6, 1.0, v76
	v_add_f32_e32 v7, 1.0, v77
	v_add_f32_e32 v13, 1.0, v78
	v_add_f32_e32 v53, 1.0, v79
	v_fma_f32 v2, v2, v6, v80
	v_fma_f32 v3, v3, v7, v81
	v_fma_f32 v4, v4, v13, v82
	v_fmac_f32_e32 v83, v5, v53
	v_cvt_pk_bf16_f32 v2, v2, v3
	v_cvt_pk_bf16_f32 v3, v4, v83
	global_store_dwordx2 v[0:1], v[2:3], off offset:2048
	v_mov_b32_e32 v2, v196
	v_mov_b32_e32 v3, v197
	v_mov_b32_e32 v4, v198
	v_mov_b32_e32 v5, v199
	v_mov_b32_e32 v76, v200
	v_mov_b32_e32 v77, v201
	v_mov_b32_e32 v78, v202
	v_mov_b32_e32 v79, v203
	v_pk_mul_f32 v[80:81], v[92:93], v[90:91] op_sel_hi:[1,0]
	v_lshl_add_u64 v[82:83], v[70:71], 0, v[60:61]
	v_lshl_add_u64 v[6:7], v[68:69], 0, v[60:61]
	v_pk_fma_f32 v[2:3], v[80:81], v[2:3], v[76:77]
	v_pk_fma_f32 v[4:5], v[84:85], v[4:5], v[78:79]
	global_store_dwordx4 v[74:75], v[2:5], off nt
	v_mov_b32_e32 v74, v204
	v_mov_b32_e32 v75, v205
	v_mov_b32_e32 v76, v206
	v_mov_b32_e32 v77, v207
	v_mov_b32_e32 v78, v208
	v_mov_b32_e32 v79, v209
	v_mov_b32_e32 v80, v210
	v_mov_b32_e32 v81, v211
	v_pk_mul_f32 v[82:83], v[88:89], v[90:91] op_sel_hi:[1,0]
	v_add_f32_e32 v6, 1.0, v74
	v_add_f32_e32 v7, 1.0, v75
	v_add_f32_e32 v13, 1.0, v76
	v_add_f32_e32 v53, 1.0, v77
	v_fma_f32 v2, v2, v6, v78
	v_fma_f32 v3, v3, v7, v79
	v_fma_f32 v4, v4, v13, v80
	v_fmac_f32_e32 v81, v5, v53
	v_cvt_pk_bf16_f32 v2, v2, v3
	v_cvt_pk_bf16_f32 v3, v4, v81
	global_store_dwordx2 v[0:1], v[2:3], off offset:2560
	v_mov_b32_e32 v2, v212
	v_mov_b32_e32 v3, v213
	v_mov_b32_e32 v4, v214
	v_mov_b32_e32 v5, v215
	v_mov_b32_e32 v74, v216
	v_mov_b32_e32 v75, v217
	v_mov_b32_e32 v76, v218
	v_mov_b32_e32 v77, v219
	v_pk_mul_f32 v[78:79], v[86:87], v[90:91] op_sel_hi:[1,0]
	v_lshl_add_u64 v[80:81], v[70:71], 0, v[62:63]
	v_lshl_add_u64 v[6:7], v[68:69], 0, v[62:63]
	v_lshl_add_u64 v[70:71], v[70:71], 0, v[64:65]
	v_pk_fma_f32 v[2:3], v[78:79], v[2:3], v[74:75]
	v_pk_fma_f32 v[4:5], v[82:83], v[4:5], v[76:77]
	global_store_dwordx4 v[72:73], v[2:5], off nt
	v_mov_b32_e32 v72, v220
	v_mov_b32_e32 v73, v221
	v_mov_b32_e32 v74, v222
	v_mov_b32_e32 v75, v223
	v_mov_b32_e32 v76, v224
	v_mov_b32_e32 v77, v225
	v_mov_b32_e32 v78, v226
	v_mov_b32_e32 v79, v227
	v_add_f32_e32 v6, 1.0, v72
	v_add_f32_e32 v7, 1.0, v73
	v_add_f32_e32 v13, 1.0, v74
	v_add_f32_e32 v53, 1.0, v75
	v_fma_f32 v2, v2, v6, v76
	v_fma_f32 v3, v3, v7, v77
	v_fma_f32 v4, v4, v13, v78
	v_fmac_f32_e32 v79, v5, v53
	v_cvt_pk_bf16_f32 v2, v2, v3
	v_cvt_pk_bf16_f32 v3, v4, v79
	global_store_dwordx2 v[0:1], v[2:3], off offset:3072
	v_mov_b32_e32 v2, v228
	v_mov_b32_e32 v3, v229
	v_mov_b32_e32 v4, v230
	v_mov_b32_e32 v5, v231
	v_mov_b32_e32 v72, v232
	v_mov_b32_e32 v73, v233
	v_mov_b32_e32 v74, v234
	v_mov_b32_e32 v75, v235
	v_pk_mul_f32 v[6:7], v[8:9], v[90:91] op_sel_hi:[1,0]
	v_pk_mul_f32 v[8:9], v[10:11], v[90:91] op_sel_hi:[1,0]
	v_lshl_add_u64 v[76:77], v[68:69], 0, v[64:65]
	v_pk_fma_f32 v[2:3], v[6:7], v[2:3], v[72:73]
	v_pk_fma_f32 v[4:5], v[8:9], v[4:5], v[74:75]
	global_store_dwordx4 v[66:67], v[2:5], off nt
	v_mov_b32_e32 v6, v236
	v_mov_b32_e32 v7, v237
	v_mov_b32_e32 v8, v238
	v_mov_b32_e32 v9, v239
	global_load_dwordx4 v[66:69], v[76:77], off
	s_waitcnt vmcnt(1)
	v_add_f32_e32 v6, 1.0, v6
	v_add_f32_e32 v7, 1.0, v7
	v_add_f32_e32 v8, 1.0, v8
	v_add_f32_e32 v9, 1.0, v9
	s_waitcnt vmcnt(0)
	v_fma_f32 v2, v2, v6, v66
	v_fma_f32 v3, v3, v7, v67
	v_fma_f32 v4, v4, v8, v68
	v_fmac_f32_e32 v69, v5, v9
	v_cvt_pk_bf16_f32 v2, v2, v3
	v_cvt_pk_bf16_f32 v3, v4, v69
	global_store_dwordx2 v[0:1], v[2:3], off offset:3584
	s_andn2_b64 exec, exec, s[12:13]
	s_cbranch_execnz .LBB0_1896

; __device__ __forceinline__ void phase_ln(const Params& p, int s) {
;     ...
;     for (int row = blockIdx.x * 8 + wid; row < 16384; row += gridDim.x * 8) {
;         const int b = row >> 12; const float* gate = mods + (size_t)s * 24576 + b * 6144 + 4096;
;         f32x4 v[8]; float sum = 0.f;
; #pragma unroll
;         for (int i = 0; i < 8; ++i) { const int c = i * 256 + lane * 4;
;             const f32x4 xv = __builtin_nontemporal_load((const f32x4*)(xin + (size_t)row * 2048 + c)), gt = *(const f32x4*)(gate + c); const f16x4 yv = __builtin_nontemporal_load((const f16x4*)(Y + (size_t)row * 2048 + c));
; #pragma unroll
;             for (int j = 0; j < 4; ++j) { v[i][j] = ALPHA_C * xv[j] + (1.0f + gt[j]) * (float)yv[j]; sum += v[i][j]; } }
.LBB0_2149:
	v_ashrrev_i32_e32 v8, 12, v12
	v_ashrrev_i32_e32 v13, 31, v12
	v_mul_i32_i24_e32 v8, 0x1800, v8
	v_lshlrev_b64 v[10:11], 13, v[12:13]
	v_lshlrev_b64 v[82:83], 12, v[12:13]
	v_ashrrev_i32_e32 v9, 31, v8
	v_lshl_add_u64 v[10:11], s[80:81], 0, v[10:11]
	v_lshl_add_u64 v[124:125], v[48:49], 0, v[82:83]
	v_lshlrev_b64 v[68:69], 2, v[8:9]
	v_mov_b32_e32 v59, v15
	v_mov_b32_e32 v61, v15
	v_mov_b32_e32 v63, v15
	v_mov_b32_e32 v65, v15
	global_load_dwordx4 v[0:3], v[16:17], off
	global_load_dwordx4 v[4:7], v[18:19], off
	v_lshl_add_u64 v[78:79], v[10:11], 0, v[14:15]
	global_load_dwordx2 v[148:149], v[124:125], off offset:2560 nt
	global_load_dwordx2 v[150:151], v[124:125], off offset:3072 nt
	global_load_dwordx2 v[152:153], v[124:125], off offset:3584 nt
	global_load_dwordx2 v[154:155], v[124:125], off offset:512 nt
	global_load_dwordx2 v[156:157], v[124:125], off offset:1024 nt
	global_load_dwordx2 v[158:159], v[124:125], off offset:1536 nt
	global_load_dwordx2 v[160:161], v[124:125], off offset:2048 nt
	v_lshl_add_u64 v[70:71], s[82:83], 0, v[68:69]
	v_mov_b32_e32 v53, v15
	v_mov_b32_e32 v55, v15
	v_mov_b32_e32 v57, v15
	v_lshl_add_u64 v[76:77], v[10:11], 0, v[58:59]
	v_lshl_add_u64 v[74:75], v[10:11], 0, v[60:61]
	v_lshl_add_u64 v[72:73], v[10:11], 0, v[62:63]
	v_lshl_add_u64 v[66:67], v[10:11], 0, v[64:65]
	global_load_dwordx4 v[8:11], v[78:79], off nt
	global_load_dwordx4 v[86:89], v[78:79], off offset:1024 nt
	global_load_dwordx4 v[92:95], v[78:79], off offset:2048 nt
	global_load_dwordx4 v[96:99], v[78:79], off offset:3072 nt
	global_load_dwordx4 v[100:103], v[76:77], off nt
	global_load_dwordx4 v[104:107], v[74:75], off nt
	global_load_dwordx4 v[108:111], v[72:73], off nt
	global_load_dwordx4 v[112:115], v[66:67], off nt
	v_lshl_add_u64 v[84:85], v[70:71], 0, s[12:13]
	v_lshl_add_u64 v[120:121], v[84:85], 0, v[14:15]
	v_lshl_add_u64 v[128:129], v[84:85], 0, v[52:53]
	v_lshl_add_u64 v[132:133], v[84:85], 0, v[54:55]
	v_lshl_add_u64 v[136:137], v[84:85], 0, v[56:57]
	v_lshl_add_u64 v[140:141], v[84:85], 0, v[58:59]
	v_lshl_add_u64 v[144:145], v[84:85], 0, v[60:61]
	v_lshl_add_u64 v[126:127], v[84:85], 0, v[62:63]
	v_lshl_add_u64 v[116:117], v[84:85], 0, v[64:65]
	global_load_dwordx4 v[116:119], v[116:117], off
	s_nop 0
	global_load_dwordx4 v[120:123], v[120:121], off
	s_nop 0
	global_load_dwordx2 v[162:163], v[124:125], off nt
	s_nop 0
	global_load_dwordx4 v[124:127], v[126:127], off
	s_nop 0
	global_load_dwordx4 v[128:131], v[128:129], off
	s_nop 0
	global_load_dwordx4 v[132:135], v[132:133], off
	s_nop 0
	global_load_dwordx4 v[136:139], v[136:137], off
	s_nop 0
	global_load_dwordx4 v[140:143], v[140:141], off
	s_nop 0
	global_load_dwordx4 v[144:147], v[144:145], off
	v_lshl_add_u64 v[68:69], s[4:5], 0, v[68:69]
	v_lshl_add_u64 v[70:71], v[68:69], 0, s[16:17]
	v_lshl_add_u64 v[84:85], v[70:71], 0, v[14:15]
	v_lshl_add_u64 v[80:81], v[68:69], 0, v[14:15]
	v_add_u32_e32 v12, s2, v12
	s_waitcnt vmcnt(23)
	v_cvt_f32_f16_e32 v178, v148
	s_waitcnt vmcnt(22)
	v_cvt_f32_f16_e32 v180, v150
	s_waitcnt vmcnt(21)
	v_cvt_f32_f16_e32 v166, v152
	v_cvt_f32_f16_sdwa v167, v152 dst_sel:DWORD dst_unused:UNUSED_PAD src0_sel:WORD_1
	v_cvt_f32_f16_e32 v164, v153
	v_cvt_f32_f16_sdwa v165, v153 dst_sel:DWORD dst_unused:UNUSED_PAD src0_sel:WORD_1
	v_cvt_f32_f16_e32 v152, v151
	v_cvt_f32_f16_sdwa v153, v151 dst_sel:DWORD dst_unused:UNUSED_PAD src0_sel:WORD_1
	v_cvt_f32_f16_sdwa v181, v150 dst_sel:DWORD dst_unused:UNUSED_PAD src0_sel:WORD_1
	s_waitcnt vmcnt(20)
	v_cvt_f32_f16_e32 v168, v154
	v_cvt_f32_f16_sdwa v169, v154 dst_sel:DWORD dst_unused:UNUSED_PAD src0_sel:WORD_1
	v_cvt_f32_f16_e32 v154, v155
	v_cvt_f32_f16_sdwa v155, v155 dst_sel:DWORD dst_unused:UNUSED_PAD src0_sel:WORD_1
	s_waitcnt vmcnt(19)
	v_cvt_f32_f16_e32 v172, v156
	v_cvt_f32_f16_sdwa v173, v156 dst_sel:DWORD dst_unused:UNUSED_PAD src0_sel:WORD_1
	v_cvt_f32_f16_e32 v156, v157
	v_cvt_f32_f16_sdwa v157, v157 dst_sel:DWORD dst_unused:UNUSED_PAD src0_sel:WORD_1
	s_waitcnt vmcnt(8)
	v_pk_add_f32 v[116:117], v[116:117], 1.0 op_sel_hi:[1,0]
	s_waitcnt vmcnt(7)
	v_pk_add_f32 v[120:121], v[120:121], 1.0 op_sel_hi:[1,0]
	s_waitcnt vmcnt(6)
	v_cvt_f32_f16_e32 v150, v162
	v_cvt_f32_f16_sdwa v151, v162 dst_sel:DWORD dst_unused:UNUSED_PAD src0_sel:WORD_1
	v_cvt_f32_f16_e32 v162, v163
	v_cvt_f32_f16_sdwa v163, v163 dst_sel:DWORD dst_unused:UNUSED_PAD src0_sel:WORD_1
	v_pk_mul_f32 v[116:117], v[116:117], v[166:167]
	v_pk_add_f32 v[118:119], v[118:119], 1.0 op_sel_hi:[1,0]
	v_pk_fma_f32 v[112:113], v[112:113], s[14:15], v[116:117] op_sel_hi:[1,0,1]
	v_pk_mul_f32 v[116:117], v[120:121], v[150:151]
	v_pk_add_f32 v[122:123], v[122:123], 1.0 op_sel_hi:[1,0]
	v_pk_mul_f32 v[118:119], v[118:119], v[164:165]
	v_pk_fma_f32 v[8:9], v[8:9], s[14:15], v[116:117] op_sel_hi:[1,0,1]
	v_pk_fma_f32 v[114:115], v[114:115], s[14:15], v[118:119] op_sel_hi:[1,0,1]
	v_pk_mul_f32 v[118:119], v[122:123], v[162:163]
	v_add_f32_e32 v13, 0, v8
	s_waitcnt vmcnt(4)
	v_pk_add_f32 v[128:129], v[128:129], 1.0 op_sel_hi:[1,0]
	v_pk_fma_f32 v[10:11], v[10:11], s[14:15], v[118:119] op_sel_hi:[1,0,1]
	v_add_f32_e32 v13, v9, v13
	v_pk_mul_f32 v[128:129], v[128:129], v[168:169]
	v_add_f32_e32 v13, v10, v13
	v_pk_add_f32 v[130:131], v[130:131], 1.0 op_sel_hi:[1,0]
	v_pk_fma_f32 v[86:87], v[86:87], s[14:15], v[128:129] op_sel_hi:[1,0,1]
	v_add_f32_e32 v13, v11, v13
	v_pk_mul_f32 v[130:131], v[130:131], v[154:155]
	v_add_f32_e32 v13, v86, v13
	s_waitcnt vmcnt(3)
; __device__ __forceinline__ void phase_ln(const Params& p, int s) {
;     ...
;             for (int j = 0; j < 4; ++j) { v[i][j] = ALPHA_C * xv[j] + (1.0f + gt[j]) * (float)yv[j]; sum += v[i][j]; } }
;         sum = wave_sum(sum); const float mean = sum * (1.0f / 2048.0f); float sq = 0.f;
; #pragma unroll
;         for (int i = 0; i < 8; ++i)
; #pragma unroll
;             for (int j = 0; j < 4; ++j) { const float d = v[i][j] - mean; sq += d * d; }
;         sq = wave_sum(sq); const float rs = rsqrtf(sq * (1.0f / 2048.0f) + 1e-5f);
	v_pk_add_f32 v[132:133], v[132:133], 1.0 op_sel_hi:[1,0]
	v_pk_fma_f32 v[88:89], v[88:89], s[14:15], v[130:131] op_sel_hi:[1,0,1]
	v_add_f32_e32 v13, v87, v13
	v_cvt_f32_f16_e32 v174, v158
	v_cvt_f32_f16_sdwa v175, v158 dst_sel:DWORD dst_unused:UNUSED_PAD src0_sel:WORD_1
	v_pk_mul_f32 v[132:133], v[132:133], v[172:173]
	v_add_f32_e32 v13, v88, v13
	v_pk_add_f32 v[134:135], v[134:135], 1.0 op_sel_hi:[1,0]
	v_pk_fma_f32 v[92:93], v[92:93], s[14:15], v[132:133] op_sel_hi:[1,0,1]
	v_add_f32_e32 v13, v89, v13
	v_cvt_f32_f16_e32 v158, v159
	v_cvt_f32_f16_sdwa v159, v159 dst_sel:DWORD dst_unused:UNUSED_PAD src0_sel:WORD_1
	v_pk_mul_f32 v[134:135], v[134:135], v[156:157]
	v_add_f32_e32 v13, v92, v13
	s_waitcnt vmcnt(2)
	v_pk_add_f32 v[136:137], v[136:137], 1.0 op_sel_hi:[1,0]
	v_pk_fma_f32 v[94:95], v[94:95], s[14:15], v[134:135] op_sel_hi:[1,0,1]
	v_add_f32_e32 v13, v93, v13
	v_cvt_f32_f16_e32 v176, v160
	v_cvt_f32_f16_sdwa v177, v160 dst_sel:DWORD dst_unused:UNUSED_PAD src0_sel:WORD_1
	v_pk_mul_f32 v[136:137], v[136:137], v[174:175]
	v_add_f32_e32 v13, v94, v13
	v_pk_add_f32 v[138:139], v[138:139], 1.0 op_sel_hi:[1,0]
	v_pk_fma_f32 v[96:97], v[96:97], s[14:15], v[136:137] op_sel_hi:[1,0,1]
	v_add_f32_e32 v13, v95, v13
	v_cvt_f32_f16_e32 v160, v161
	v_cvt_f32_f16_sdwa v161, v161 dst_sel:DWORD dst_unused:UNUSED_PAD src0_sel:WORD_1
	v_pk_mul_f32 v[138:139], v[138:139], v[158:159]
	v_add_f32_e32 v13, v96, v13
	s_waitcnt vmcnt(1)
	v_pk_add_f32 v[140:141], v[140:141], 1.0 op_sel_hi:[1,0]
	v_pk_fma_f32 v[98:99], v[98:99], s[14:15], v[138:139] op_sel_hi:[1,0,1]
	v_add_f32_e32 v13, v97, v13
	v_cvt_f32_f16_sdwa v179, v148 dst_sel:DWORD dst_unused:UNUSED_PAD src0_sel:WORD_1
	v_pk_mul_f32 v[140:141], v[140:141], v[176:177]
	v_add_f32_e32 v13, v98, v13
	v_pk_add_f32 v[142:143], v[142:143], 1.0 op_sel_hi:[1,0]
	v_pk_fma_f32 v[100:101], v[100:101], s[14:15], v[140:141] op_sel_hi:[1,0,1]
	v_add_f32_e32 v13, v99, v13
	v_cvt_f32_f16_e32 v148, v149
	v_cvt_f32_f16_sdwa v149, v149 dst_sel:DWORD dst_unused:UNUSED_PAD src0_sel:WORD_1
	v_pk_mul_f32 v[142:143], v[142:143], v[160:161]
	v_add_f32_e32 v13, v100, v13
	s_waitcnt vmcnt(0)
	v_pk_add_f32 v[144:145], v[144:145], 1.0 op_sel_hi:[1,0]
	v_pk_fma_f32 v[102:103], v[102:103], s[14:15], v[142:143] op_sel_hi:[1,0,1]
	v_add_f32_e32 v13, v101, v13
	v_pk_mul_f32 v[144:145], v[144:145], v[178:179]
	v_add_f32_e32 v13, v102, v13
	v_pk_add_f32 v[146:147], v[146:147], 1.0 op_sel_hi:[1,0]
	v_pk_fma_f32 v[104:105], v[104:105], s[14:15], v[144:145] op_sel_hi:[1,0,1]
	v_add_f32_e32 v13, v103, v13
	v_pk_mul_f32 v[146:147], v[146:147], v[148:149]
	v_add_f32_e32 v13, v104, v13
	v_pk_add_f32 v[124:125], v[124:125], 1.0 op_sel_hi:[1,0]
	v_pk_fma_f32 v[106:107], v[106:107], s[14:15], v[146:147] op_sel_hi:[1,0,1]
	v_add_f32_e32 v13, v105, v13
	v_pk_mul_f32 v[124:125], v[124:125], v[180:181]
	v_add_f32_e32 v13, v106, v13
	v_pk_add_f32 v[126:127], v[126:127], 1.0 op_sel_hi:[1,0]
	v_pk_fma_f32 v[108:109], v[108:109], s[14:15], v[124:125] op_sel_hi:[1,0,1]
	v_add_f32_e32 v13, v107, v13
	v_pk_mul_f32 v[126:127], v[126:127], v[152:153]
	v_add_f32_e32 v13, v108, v13
	v_pk_fma_f32 v[110:111], v[110:111], s[14:15], v[126:127] op_sel_hi:[1,0,1]
	v_add_f32_e32 v13, v109, v13
	v_add_f32_e32 v13, v110, v13
	v_add_f32_e32 v13, v111, v13
	v_add_f32_e32 v13, v112, v13
	v_add_f32_e32 v13, v113, v13
	v_add_f32_e32 v13, v114, v13
	v_add_f32_e32 v13, v115, v13
	s_nop 1
	v_add_f32_dpp v13, v13, v13 quad_perm:[1,0,3,2] row_mask:0xf bank_mask:0xf bound_ctrl:1
	s_nop 1
	v_add_f32_dpp v13, v13, v13 quad_perm:[2,3,0,1] row_mask:0xf bank_mask:0xf bound_ctrl:1
	s_nop 1
	v_add_f32_dpp v13, v13, v13 row_half_mirror row_mask:0xf bank_mask:0xf bound_ctrl:1
	s_nop 1
	v_add_f32_dpp v13, v13, v13 row_mirror row_mask:0xf bank_mask:0xf bound_ctrl:1
	s_nop 0
	v_readlane_b32 s22, v13, 16
	v_readlane_b32 s23, v13, 48
	v_readlane_b32 s20, v13, 0
	v_readlane_b32 s21, v13, 32
	v_mov_b32_e32 v116, s22
	v_mov_b32_e32 v117, s23
	v_pk_add_f32 v[116:117], s[20:21], v[116:117]
	s_nop 0
	v_add_f32_e32 v13, v116, v117
	v_mul_f32_e32 v90, 0x3a000000, v13
	v_pk_add_f32 v[116:117], v[8:9], v[90:91] op_sel_hi:[1,0] neg_lo:[0,1] neg_hi:[0,1]
	v_pk_add_f32 v[118:119], v[10:11], v[90:91] op_sel_hi:[1,0] neg_lo:[0,1] neg_hi:[0,1]
	v_pk_add_f32 v[128:129], v[96:97], v[90:91] op_sel_hi:[1,0] neg_lo:[0,1] neg_hi:[0,1]
	v_pk_mul_f32 v[96:97], v[116:117], v[116:117]
	v_pk_add_f32 v[130:131], v[98:99], v[90:91] op_sel_hi:[1,0] neg_lo:[0,1] neg_hi:[0,1]
	v_pk_mul_f32 v[98:99], v[118:119], v[118:119]
	v_add_f32_e32 v13, v96, v97
	v_pk_add_f32 v[120:121], v[86:87], v[90:91] op_sel_hi:[1,0] neg_lo:[0,1] neg_hi:[0,1]
	v_add_f32_e32 v13, v98, v13
	v_pk_add_f32 v[132:133], v[100:101], v[90:91] op_sel_hi:[1,0] neg_lo:[0,1] neg_hi:[0,1]
	v_pk_mul_f32 v[100:101], v[120:121], v[120:121]
	v_add_f32_e32 v13, v99, v13
	v_pk_add_f32 v[122:123], v[88:89], v[90:91] op_sel_hi:[1,0] neg_lo:[0,1] neg_hi:[0,1]
	v_add_f32_e32 v13, v100, v13
	v_pk_add_f32 v[134:135], v[102:103], v[90:91] op_sel_hi:[1,0] neg_lo:[0,1] neg_hi:[0,1]
	v_pk_mul_f32 v[102:103], v[122:123], v[122:123]
	v_add_f32_e32 v13, v101, v13
	v_pk_add_f32 v[124:125], v[92:93], v[90:91] op_sel_hi:[1,0] neg_lo:[0,1] neg_hi:[0,1]
	v_add_f32_e32 v13, v102, v13
	v_pk_add_f32 v[92:93], v[104:105], v[90:91] op_sel_hi:[1,0] neg_lo:[0,1] neg_hi:[0,1]
	v_pk_mul_f32 v[104:105], v[124:125], v[124:125]
	v_add_f32_e32 v13, v103, v13
	v_pk_add_f32 v[126:127], v[94:95], v[90:91] op_sel_hi:[1,0] neg_lo:[0,1] neg_hi:[0,1]
	v_add_f32_e32 v13, v104, v13
	v_pk_add_f32 v[94:95], v[106:107], v[90:91] op_sel_hi:[1,0] neg_lo:[0,1] neg_hi:[0,1]
	v_pk_mul_f32 v[106:107], v[126:127], v[126:127]
; __device__ __forceinline__ unsigned cvt_pk_bf16(float lo, float hi) { unsigned r; asm volatile("v_cvt_pk_bf16_f32 %0, %1, %2" : "=v"(r) : "v"(lo), "v"(hi)); return r; }
; __device__ __forceinline__ void phase_ln(const Params& p, int s) {
;     ...
;         sq = wave_sum(sq); const float rs = rsqrtf(sq * (1.0f / 2048.0f) + 1e-5f);
; #pragma unroll
;         for (int i = 0; i < 8; ++i) { const int c = i * 256 + lane * 4; const f32x4 g4 = *(const f32x4*)(lg + c), b4 = *(const f32x4*)(lb + c); f32x4 xn;
; #pragma unroll
;             for (int j = 0; j < 4; ++j) xn[j] = (v[i][j] - mean) * rs * g4[j] + b4[j];
;             __builtin_nontemporal_store(xn, (f32x4*)(p.out + (size_t)row * 2048 + c));
;             if (s < 3) { const float* mn = mods + (size_t)(s + 1) * 24576 + b * 6144; const f32x4 sh = *(const f32x4*)(mn + c), scl = *(const f32x4*)(mn + 2048 + c);
;                 u32x2 o; o[0] = cvt_pk_bf16(xn[0] * (1.f + scl[0]) + sh[0], xn[1] * (1.f + scl[1]) + sh[1]); o[1] = cvt_pk_bf16(xn[2] * (1.f + scl[2]) + sh[2], xn[3] * (1.f + scl[3]) + sh[3]);
;                 *(u32x2*)(H + (size_t)row * 2048 + c) = o; } }
	v_add_f32_e32 v13, v105, v13
	v_add_f32_e32 v13, v106, v13
	v_pk_add_f32 v[86:87], v[108:109], v[90:91] op_sel_hi:[1,0] neg_lo:[0,1] neg_hi:[0,1]
	v_pk_mul_f32 v[108:109], v[128:129], v[128:129]
	v_add_f32_e32 v13, v107, v13
	v_add_f32_e32 v13, v108, v13
	v_pk_add_f32 v[88:89], v[110:111], v[90:91] op_sel_hi:[1,0] neg_lo:[0,1] neg_hi:[0,1]
	v_pk_mul_f32 v[110:111], v[130:131], v[130:131]
	v_add_f32_e32 v13, v109, v13
	v_add_f32_e32 v13, v110, v13
	v_pk_add_f32 v[8:9], v[112:113], v[90:91] op_sel_hi:[1,0] neg_lo:[0,1] neg_hi:[0,1]
	v_pk_mul_f32 v[112:113], v[132:133], v[132:133]
	v_add_f32_e32 v13, v111, v13
	v_add_f32_e32 v13, v112, v13
	v_pk_add_f32 v[10:11], v[114:115], v[90:91] op_sel_hi:[1,0] neg_lo:[0,1] neg_hi:[0,1]
	v_pk_mul_f32 v[114:115], v[134:135], v[134:135]
	v_add_f32_e32 v13, v113, v13
	v_add_f32_e32 v13, v114, v13
	v_pk_mul_f32 v[136:137], v[92:93], v[92:93]
	v_add_f32_e32 v13, v115, v13
	v_add_f32_e32 v13, v136, v13
	v_pk_mul_f32 v[138:139], v[94:95], v[94:95]
	v_add_f32_e32 v13, v137, v13
	v_add_f32_e32 v13, v138, v13
	v_pk_mul_f32 v[140:141], v[86:87], v[86:87]
	v_add_f32_e32 v13, v139, v13
	v_add_f32_e32 v13, v140, v13
	v_pk_mul_f32 v[142:143], v[88:89], v[88:89]
	v_add_f32_e32 v13, v141, v13
	v_add_f32_e32 v13, v142, v13
	v_pk_mul_f32 v[144:145], v[8:9], v[8:9]
	v_add_f32_e32 v13, v143, v13
	v_add_f32_e32 v13, v144, v13
	v_pk_mul_f32 v[146:147], v[10:11], v[10:11]
	v_add_f32_e32 v13, v145, v13
	v_add_f32_e32 v13, v146, v13
	v_add_f32_e32 v13, v147, v13
	s_nop 1
	v_add_f32_dpp v13, v13, v13 quad_perm:[1,0,3,2] row_mask:0xf bank_mask:0xf bound_ctrl:1
	s_nop 1
	v_add_f32_dpp v13, v13, v13 quad_perm:[2,3,0,1] row_mask:0xf bank_mask:0xf bound_ctrl:1
	s_nop 1
	v_add_f32_dpp v13, v13, v13 row_half_mirror row_mask:0xf bank_mask:0xf bound_ctrl:1
	s_nop 1
	v_add_f32_dpp v13, v13, v13 row_mirror row_mask:0xf bank_mask:0xf bound_ctrl:1
	s_nop 0
	v_readlane_b32 s22, v13, 16
	v_readlane_b32 s23, v13, 48
	v_readlane_b32 s20, v13, 0
	v_readlane_b32 s21, v13, 32
	v_mov_b32_e32 v96, s22
	v_mov_b32_e32 v97, s23
	v_pk_add_f32 v[96:97], s[20:21], v[96:97]
	s_nop 0
	v_add_f32_e32 v13, v96, v97
	v_fmamk_f32 v13, v13, 0x3a000000, v91
	v_mul_f32_e32 v90, 0x4b800000, v13
	v_cmp_gt_f32_e32 vcc, s3, v13
	s_nop 1
	v_cndmask_b32_e32 v13, v13, v90, vcc
	v_rsq_f32_e32 v13, v13
	s_nop 0
	v_mul_f32_e32 v90, 0x45800000, v13
	v_cndmask_b32_e32 v90, v13, v90, vcc
	v_pk_mul_f32 v[96:97], v[116:117], v[90:91] op_sel_hi:[1,0]
	v_pk_mul_f32 v[98:99], v[118:119], v[90:91] op_sel_hi:[1,0]
	v_pk_fma_f32 v[4:5], v[0:1], v[96:97], v[4:5]
	v_pk_fma_f32 v[6:7], v[2:3], v[98:99], v[6:7]
	global_load_dwordx4 v[104:107], v[84:85], off
	global_load_dwordx4 v[108:111], v[80:81], off
	global_load_dwordx4 v[112:115], v[20:21], off
	global_load_dwordx4 v[116:119], v[22:23], off
	v_lshl_add_u64 v[136:137], v[70:71], 0, v[52:53]
	global_load_dwordx4 v[136:139], v[136:137], off
	global_load_dwordx4 v[140:143], v[80:81], off offset:1024
	global_load_dwordx4 v[144:147], v[24:25], off
	global_load_dwordx4 v[148:151], v[26:27], off
	v_lshl_add_u64 v[152:153], v[70:71], 0, v[54:55]
	global_load_dwordx4 v[152:155], v[152:153], off
	global_load_dwordx4 v[156:159], v[80:81], off offset:2048
	global_load_dwordx4 v[160:163], v[28:29], off
	global_load_dwordx4 v[164:167], v[30:31], off
	v_lshl_add_u64 v[172:173], v[70:71], 0, v[56:57]
	global_load_dwordx4 v[172:175], v[172:173], off
	global_load_dwordx4 v[176:179], v[80:81], off offset:3072
	global_load_dwordx4 v[180:183], v[32:33], off
	global_load_dwordx4 v[184:187], v[34:35], off
	v_lshl_add_u64 v[188:189], v[70:71], 0, v[58:59]
	global_load_dwordx4 v[188:191], v[188:189], off
	v_lshl_add_u64 v[192:193], v[68:69], 0, v[58:59]
	global_load_dwordx4 v[192:195], v[192:193], off
	global_load_dwordx4 v[196:199], v[36:37], off
	global_load_dwordx4 v[200:203], v[38:39], off
	v_lshl_add_u64 v[204:205], v[70:71], 0, v[60:61]
	global_load_dwordx4 v[204:207], v[204:205], off
	v_lshl_add_u64 v[208:209], v[68:69], 0, v[60:61]
	global_load_dwordx4 v[208:211], v[208:209], off
	global_load_dwordx4 v[212:215], v[40:41], off
	global_load_dwordx4 v[216:219], v[42:43], off
	v_lshl_add_u64 v[220:221], v[70:71], 0, v[62:63]
	global_load_dwordx4 v[220:223], v[220:221], off
	v_lshl_add_u64 v[224:225], v[68:69], 0, v[62:63]
	global_load_dwordx4 v[224:227], v[224:225], off
	global_load_dwordx4 v[228:231], v[44:45], off
	global_load_dwordx4 v[232:235], v[46:47], off
	v_lshl_add_u64 v[236:237], v[70:71], 0, v[64:65]
	global_load_dwordx4 v[236:239], v[236:237], off
	s_waitcnt vmcnt(0)
; __device__ __forceinline__ unsigned cvt_pk_bf16(float lo, float hi) { unsigned r; asm volatile("v_cvt_pk_bf16_f32 %0, %1, %2" : "=v"(r) : "v"(lo), "v"(hi)); return r; }
; __device__ __forceinline__ void phase_ln(const Params& p, int s) {
;     ...
;         for (int i = 0; i < 8; ++i) { const int c = i * 256 + lane * 4; const f32x4 g4 = *(const f32x4*)(lg + c), b4 = *(const f32x4*)(lb + c); f32x4 xn;
; #pragma unroll
;             for (int j = 0; j < 4; ++j) xn[j] = (v[i][j] - mean) * rs * g4[j] + b4[j];
;             __builtin_nontemporal_store(xn, (f32x4*)(p.out + (size_t)row * 2048 + c));
;             if (s < 3) { const float* mn = mods + (size_t)(s + 1) * 24576 + b * 6144; const f32x4 sh = *(const f32x4*)(mn + c), scl = *(const f32x4*)(mn + 2048 + c);
;                 u32x2 o; o[0] = cvt_pk_bf16(xn[0] * (1.f + scl[0]) + sh[0], xn[1] * (1.f + scl[1]) + sh[1]); o[1] = cvt_pk_bf16(xn[2] * (1.f + scl[2]) + sh[2], xn[3] * (1.f + scl[3]) + sh[3]);
;                 *(u32x2*)(H + (size_t)row * 2048 + c) = o; } }
	global_store_dwordx4 v[78:79], v[4:7], off nt
	v_mov_b32_e32 v96, v104
	v_mov_b32_e32 v97, v105
	v_mov_b32_e32 v98, v106
	v_mov_b32_e32 v99, v107
	v_mov_b32_e32 v100, v108
	v_mov_b32_e32 v101, v109
	v_mov_b32_e32 v102, v110
	v_mov_b32_e32 v103, v111
	v_lshl_add_u64 v[0:1], v[50:51], 0, v[82:83]
	v_cmp_lt_i32_e32 vcc, s15, v12
	s_or_b64 s[6:7], vcc, s[6:7]
	v_add_f32_e32 v2, 1.0, v96
	v_add_f32_e32 v3, 1.0, v97
	v_add_f32_e32 v13, 1.0, v98
	v_add_f32_e32 v82, 1.0, v99
	v_fma_f32 v2, v2, v4, v100
	v_fma_f32 v3, v3, v5, v101
	v_fma_f32 v4, v13, v6, v102
	v_fmac_f32_e32 v103, v82, v7
	v_cvt_pk_bf16_f32 v2, v2, v3
	v_cvt_pk_bf16_f32 v3, v4, v103
	global_store_dwordx2 v[0:1], v[2:3], off
	v_mov_b32_e32 v2, v112
	v_mov_b32_e32 v3, v113
	v_mov_b32_e32 v4, v114
	v_mov_b32_e32 v5, v115
	v_mov_b32_e32 v82, v116
	v_mov_b32_e32 v83, v117
	v_mov_b32_e32 v84, v118
	v_mov_b32_e32 v85, v119
	v_pk_mul_f32 v[96:97], v[120:121], v[90:91] op_sel_hi:[1,0]
	v_pk_mul_f32 v[98:99], v[122:123], v[90:91] op_sel_hi:[1,0]
	v_lshl_add_u64 v[6:7], v[70:71], 0, v[52:53]
	v_pk_fma_f32 v[2:3], v[2:3], v[96:97], v[82:83]
	v_pk_fma_f32 v[4:5], v[4:5], v[98:99], v[84:85]
	global_store_dwordx4 v[78:79], v[2:5], off offset:1024 nt
	v_mov_b32_e32 v82, v136
	v_mov_b32_e32 v83, v137
	v_mov_b32_e32 v84, v138
	v_mov_b32_e32 v85, v139
	v_mov_b32_e32 v96, v140
	v_mov_b32_e32 v97, v141
	v_mov_b32_e32 v98, v142
	v_mov_b32_e32 v99, v143
	v_add_f32_e32 v6, 1.0, v82
	v_add_f32_e32 v7, 1.0, v83
	v_add_f32_e32 v13, 1.0, v84
	v_add_f32_e32 v53, 1.0, v85
	v_fma_f32 v2, v2, v6, v96
	v_fma_f32 v3, v3, v7, v97
	v_fma_f32 v4, v4, v13, v98
	v_fmac_f32_e32 v99, v5, v53
	v_cvt_pk_bf16_f32 v2, v2, v3
	v_cvt_pk_bf16_f32 v3, v4, v99
	global_store_dwordx2 v[0:1], v[2:3], off offset:512
	v_mov_b32_e32 v2, v144
	v_mov_b32_e32 v3, v145
	v_mov_b32_e32 v4, v146
	v_mov_b32_e32 v5, v147
	v_mov_b32_e32 v82, v148
	v_mov_b32_e32 v83, v149
	v_mov_b32_e32 v84, v150
	v_mov_b32_e32 v85, v151
	v_pk_mul_f32 v[96:97], v[124:125], v[90:91] op_sel_hi:[1,0]
	v_pk_mul_f32 v[98:99], v[126:127], v[90:91] op_sel_hi:[1,0]
	v_lshl_add_u64 v[6:7], v[70:71], 0, v[54:55]
	v_pk_fma_f32 v[2:3], v[96:97], v[2:3], v[82:83]
	v_pk_fma_f32 v[4:5], v[98:99], v[4:5], v[84:85]
	global_store_dwordx4 v[78:79], v[2:5], off offset:2048 nt
	v_mov_b32_e32 v82, v152
	v_mov_b32_e32 v83, v153
	v_mov_b32_e32 v84, v154
	v_mov_b32_e32 v85, v155
	v_mov_b32_e32 v96, v156
	v_mov_b32_e32 v97, v157
	v_mov_b32_e32 v98, v158
	v_mov_b32_e32 v99, v159
	v_add_f32_e32 v6, 1.0, v82
	v_add_f32_e32 v7, 1.0, v83
	v_add_f32_e32 v13, 1.0, v84
	v_add_f32_e32 v53, 1.0, v85
	v_fma_f32 v2, v2, v6, v96
	v_fma_f32 v3, v3, v7, v97
	v_fma_f32 v4, v4, v13, v98
	v_fmac_f32_e32 v99, v5, v53
	v_cvt_pk_bf16_f32 v2, v2, v3
	v_cvt_pk_bf16_f32 v3, v4, v99
	global_store_dwordx2 v[0:1], v[2:3], off offset:1024
	v_mov_b32_e32 v2, v160
	v_mov_b32_e32 v3, v161
	v_mov_b32_e32 v4, v162
	v_mov_b32_e32 v5, v163
	v_mov_b32_e32 v82, v164
	v_mov_b32_e32 v83, v165
	v_mov_b32_e32 v84, v166
	v_mov_b32_e32 v85, v167
	v_pk_mul_f32 v[96:97], v[128:129], v[90:91] op_sel_hi:[1,0]
	v_pk_mul_f32 v[98:99], v[130:131], v[90:91] op_sel_hi:[1,0]
	v_lshl_add_u64 v[6:7], v[70:71], 0, v[56:57]
	v_pk_fma_f32 v[2:3], v[96:97], v[2:3], v[82:83]
	v_pk_fma_f32 v[4:5], v[98:99], v[4:5], v[84:85]
	global_store_dwordx4 v[78:79], v[2:5], off offset:3072 nt
	v_mov_b32_e32 v82, v172
	v_mov_b32_e32 v83, v173
	v_mov_b32_e32 v84, v174
	v_mov_b32_e32 v85, v175
	v_mov_b32_e32 v96, v176
	v_mov_b32_e32 v97, v177
	v_mov_b32_e32 v98, v178
	v_mov_b32_e32 v99, v179
	v_add_f32_e32 v6, 1.0, v82
	v_add_f32_e32 v7, 1.0, v83
	v_add_f32_e32 v13, 1.0, v84
	v_add_f32_e32 v53, 1.0, v85
	v_fma_f32 v2, v2, v6, v96
	v_fma_f32 v3, v3, v7, v97
	v_fma_f32 v4, v4, v13, v98
	v_fmac_f32_e32 v99, v5, v53
	v_cvt_pk_bf16_f32 v2, v2, v3
	v_cvt_pk_bf16_f32 v3, v4, v99
	global_store_dwordx2 v[0:1], v[2:3], off offset:1536
	v_mov_b32_e32 v2, v180
	v_mov_b32_e32 v3, v181
	v_mov_b32_e32 v4, v182
	v_mov_b32_e32 v5, v183
	v_mov_b32_e32 v78, v184
	v_mov_b32_e32 v79, v185
	v_mov_b32_e32 v80, v186
	v_mov_b32_e32 v81, v187
	v_pk_mul_f32 v[82:83], v[132:133], v[90:91] op_sel_hi:[1,0]
; __device__ __forceinline__ unsigned cvt_pk_bf16(float lo, float hi) { unsigned r; asm volatile("v_cvt_pk_bf16_f32 %0, %1, %2" : "=v"(r) : "v"(lo), "v"(hi)); return r; }
; __device__ __forceinline__ void phase_ln(const Params& p, int s) {
;     ...
;         for (int i = 0; i < 8; ++i) { const int c = i * 256 + lane * 4; const f32x4 g4 = *(const f32x4*)(lg + c), b4 = *(const f32x4*)(lb + c); f32x4 xn;
; #pragma unroll
;             for (int j = 0; j < 4; ++j) xn[j] = (v[i][j] - mean) * rs * g4[j] + b4[j];
;             __builtin_nontemporal_store(xn, (f32x4*)(p.out + (size_t)row * 2048 + c));
;             if (s < 3) { const float* mn = mods + (size_t)(s + 1) * 24576 + b * 6144; const f32x4 sh = *(const f32x4*)(mn + c), scl = *(const f32x4*)(mn + 2048 + c);
;                 u32x2 o; o[0] = cvt_pk_bf16(xn[0] * (1.f + scl[0]) + sh[0], xn[1] * (1.f + scl[1]) + sh[1]); o[1] = cvt_pk_bf16(xn[2] * (1.f + scl[2]) + sh[2], xn[3] * (1.f + scl[3]) + sh[3]);
;                 *(u32x2*)(H + (size_t)row * 2048 + c) = o; } }
	v_pk_mul_f32 v[96:97], v[134:135], v[90:91] op_sel_hi:[1,0]
	v_lshl_add_u64 v[84:85], v[70:71], 0, v[58:59]
	v_lshl_add_u64 v[6:7], v[68:69], 0, v[58:59]
	v_pk_fma_f32 v[2:3], v[82:83], v[2:3], v[78:79]
	v_pk_fma_f32 v[4:5], v[96:97], v[4:5], v[80:81]
	global_store_dwordx4 v[76:77], v[2:5], off nt
	v_mov_b32_e32 v76, v188
	v_mov_b32_e32 v77, v189
	v_mov_b32_e32 v78, v190
	v_mov_b32_e32 v79, v191
	v_mov_b32_e32 v80, v192
	v_mov_b32_e32 v81, v193
	v_mov_b32_e32 v82, v194
	v_mov_b32_e32 v83, v195
	v_pk_mul_f32 v[84:85], v[94:95], v[90:91] op_sel_hi:[1,0]
	v_add_f32_e32 v6, 1.0, v76
	v_add_f32_e32 v7, 1.0, v77
	v_add_f32_e32 v13, 1.0, v78
	v_add_f32_e32 v53, 1.0, v79
	v_fma_f32 v2, v2, v6, v80
	v_fma_f32 v3, v3, v7, v81
	v_fma_f32 v4, v4, v13, v82
	v_fmac_f32_e32 v83, v5, v53
	v_cvt_pk_bf16_f32 v2, v2, v3
	v_cvt_pk_bf16_f32 v3, v4, v83
	global_store_dwordx2 v[0:1], v[2:3], off offset:2048
	v_mov_b32_e32 v2, v196
	v_mov_b32_e32 v3, v197
	v_mov_b32_e32 v4, v198
	v_mov_b32_e32 v5, v199
	v_mov_b32_e32 v76, v200
	v_mov_b32_e32 v77, v201
	v_mov_b32_e32 v78, v202
	v_mov_b32_e32 v79, v203
	v_pk_mul_f32 v[80:81], v[92:93], v[90:91] op_sel_hi:[1,0]
	v_lshl_add_u64 v[82:83], v[70:71], 0, v[60:61]
	v_lshl_add_u64 v[6:7], v[68:69], 0, v[60:61]
	v_pk_fma_f32 v[2:3], v[80:81], v[2:3], v[76:77]
	v_pk_fma_f32 v[4:5], v[84:85], v[4:5], v[78:79]
	global_store_dwordx4 v[74:75], v[2:5], off nt
	v_mov_b32_e32 v74, v204
	v_mov_b32_e32 v75, v205
	v_mov_b32_e32 v76, v206
	v_mov_b32_e32 v77, v207
	v_mov_b32_e32 v78, v208
	v_mov_b32_e32 v79, v209
	v_mov_b32_e32 v80, v210
	v_mov_b32_e32 v81, v211
	v_pk_mul_f32 v[82:83], v[88:89], v[90:91] op_sel_hi:[1,0]
	v_add_f32_e32 v6, 1.0, v74
	v_add_f32_e32 v7, 1.0, v75
	v_add_f32_e32 v13, 1.0, v76
	v_add_f32_e32 v53, 1.0, v77
	v_fma_f32 v2, v2, v6, v78
	v_fma_f32 v3, v3, v7, v79
	v_fma_f32 v4, v4, v13, v80
	v_fmac_f32_e32 v81, v5, v53
	v_cvt_pk_bf16_f32 v2, v2, v3
	v_cvt_pk_bf16_f32 v3, v4, v81
	global_store_dwordx2 v[0:1], v[2:3], off offset:2560
	v_mov_b32_e32 v2, v212
	v_mov_b32_e32 v3, v213
	v_mov_b32_e32 v4, v214
	v_mov_b32_e32 v5, v215
	v_mov_b32_e32 v74, v216
	v_mov_b32_e32 v75, v217
	v_mov_b32_e32 v76, v218
	v_mov_b32_e32 v77, v219
	v_pk_mul_f32 v[78:79], v[86:87], v[90:91] op_sel_hi:[1,0]
	v_lshl_add_u64 v[80:81], v[70:71], 0, v[62:63]
	v_lshl_add_u64 v[6:7], v[68:69], 0, v[62:63]
	v_lshl_add_u64 v[70:71], v[70:71], 0, v[64:65]
	v_pk_fma_f32 v[2:3], v[78:79], v[2:3], v[74:75]
	v_pk_fma_f32 v[4:5], v[82:83], v[4:5], v[76:77]
	global_store_dwordx4 v[72:73], v[2:5], off nt
	v_mov_b32_e32 v72, v220
	v_mov_b32_e32 v73, v221
	v_mov_b32_e32 v74, v222
	v_mov_b32_e32 v75, v223
	v_mov_b32_e32 v76, v224
	v_mov_b32_e32 v77, v225
	v_mov_b32_e32 v78, v226
	v_mov_b32_e32 v79, v227
	v_add_f32_e32 v6, 1.0, v72
	v_add_f32_e32 v7, 1.0, v73
	v_add_f32_e32 v13, 1.0, v74
	v_add_f32_e32 v53, 1.0, v75
	v_fma_f32 v2, v2, v6, v76
	v_fma_f32 v3, v3, v7, v77
	v_fma_f32 v4, v4, v13, v78
	v_fmac_f32_e32 v79, v5, v53
	v_cvt_pk_bf16_f32 v2, v2, v3
	v_cvt_pk_bf16_f32 v3, v4, v79
	global_store_dwordx2 v[0:1], v[2:3], off offset:3072
	v_mov_b32_e32 v2, v228
	v_mov_b32_e32 v3, v229
	v_mov_b32_e32 v4, v230
	v_mov_b32_e32 v5, v231
	v_mov_b32_e32 v72, v232
	v_mov_b32_e32 v73, v233
	v_mov_b32_e32 v74, v234
	v_mov_b32_e32 v75, v235
	v_pk_mul_f32 v[6:7], v[8:9], v[90:91] op_sel_hi:[1,0]
	v_pk_mul_f32 v[8:9], v[10:11], v[90:91] op_sel_hi:[1,0]
	v_lshl_add_u64 v[76:77], v[68:69], 0, v[64:65]
	v_pk_fma_f32 v[2:3], v[6:7], v[2:3], v[72:73]
	v_pk_fma_f32 v[4:5], v[8:9], v[4:5], v[74:75]
	global_store_dwordx4 v[66:67], v[2:5], off nt
	v_mov_b32_e32 v6, v236
	v_mov_b32_e32 v7, v237
	v_mov_b32_e32 v8, v238
	v_mov_b32_e32 v9, v239
	global_load_dwordx4 v[66:69], v[76:77], off
	s_waitcnt vmcnt(1)
	v_add_f32_e32 v6, 1.0, v6
	v_add_f32_e32 v7, 1.0, v7
	v_add_f32_e32 v8, 1.0, v8
	v_add_f32_e32 v9, 1.0, v9
	s_waitcnt vmcnt(0)
	v_fma_f32 v2, v2, v6, v66
	v_fma_f32 v3, v3, v7, v67
	v_fma_f32 v4, v4, v8, v68
	v_fmac_f32_e32 v69, v5, v9
	v_cvt_pk_bf16_f32 v2, v2, v3
	v_cvt_pk_bf16_f32 v3, v4, v69
	global_store_dwordx2 v[0:1], v[2:3], off offset:3584
	s_andn2_b64 exec, exec, s[6:7]
	s_cbranch_execnz .LBB0_2149

; __device__ __forceinline__ void phase_ln(const Params& p, int s) {
;     ...
;     for (int row = blockIdx.x * 8 + wid; row < 16384; row += gridDim.x * 8) {
;         const int b = row >> 12; const float* gate = mods + (size_t)s * 24576 + b * 6144 + 4096;
;         f32x4 v[8]; float sum = 0.f;
; #pragma unroll
;         for (int i = 0; i < 8; ++i) { const int c = i * 256 + lane * 4;
;             const f32x4 xv = __builtin_nontemporal_load((const f32x4*)(xin + (size_t)row * 2048 + c)), gt = *(const f32x4*)(gate + c); const f16x4 yv = __builtin_nontemporal_load((const f16x4*)(Y + (size_t)row * 2048 + c));
; #pragma unroll
;             for (int j = 0; j < 4; ++j) { v[i][j] = ALPHA_C * xv[j] + (1.0f + gt[j]) * (float)yv[j]; sum += v[i][j]; } }
.LBB0_2336:
	v_ashrrev_i32_e32 v9, 31, v8
	v_lshlrev_b64 v[64:65], 12, v[8:9]
	v_lshl_add_u64 v[112:113], v[44:45], 0, v[64:65]
	global_load_dwordx4 v[0:3], v[12:13], off
	global_load_dwordx4 v[4:7], v[14:15], off
	global_load_dwordx2 v[136:137], v[112:113], off offset:2560 nt
	global_load_dwordx2 v[138:139], v[112:113], off offset:3072 nt
	global_load_dwordx2 v[140:141], v[112:113], off offset:3584 nt
	v_ashrrev_i32_e32 v60, 12, v8
	v_mul_i32_i24_e32 v60, 0x1800, v60
	v_lshlrev_b64 v[62:63], 13, v[8:9]
	v_ashrrev_i32_e32 v61, 31, v60
	v_lshl_add_u64 v[72:73], s[80:81], 0, v[62:63]
	v_mov_b32_e32 v53, v11
	v_mov_b32_e32 v55, v11
	v_mov_b32_e32 v57, v11
	v_mov_b32_e32 v59, v11
	v_lshl_add_u64 v[74:75], v[60:61], 2, s[82:83]
	v_lshl_add_u64 v[68:69], v[72:73], 0, v[10:11]
	v_mov_b32_e32 v47, v11
	v_mov_b32_e32 v49, v11
	v_mov_b32_e32 v51, v11
	v_lshl_add_u64 v[66:67], v[72:73], 0, v[52:53]
	global_load_dwordx2 v[142:143], v[112:113], off offset:512 nt
	global_load_dwordx2 v[144:145], v[112:113], off offset:1024 nt
	global_load_dwordx2 v[146:147], v[112:113], off offset:1536 nt
	global_load_dwordx2 v[148:149], v[112:113], off offset:2048 nt
	v_lshl_add_u64 v[64:65], v[72:73], 0, v[54:55]
	v_lshl_add_u64 v[62:63], v[72:73], 0, v[56:57]
	v_lshl_add_u64 v[60:61], v[72:73], 0, v[58:59]
	v_lshl_add_u64 v[104:105], v[74:75], 0, s[2:3]
	global_load_dwordx4 v[72:75], v[68:69], off nt
	global_load_dwordx4 v[76:79], v[68:69], off offset:1024 nt
	global_load_dwordx4 v[80:83], v[68:69], off offset:2048 nt
	global_load_dwordx4 v[84:87], v[68:69], off offset:3072 nt
	global_load_dwordx4 v[88:91], v[66:67], off nt
	global_load_dwordx4 v[92:95], v[64:65], off nt
	global_load_dwordx4 v[96:99], v[62:63], off nt
	global_load_dwordx4 v[100:103], v[60:61], off nt
	v_lshl_add_u64 v[108:109], v[104:105], 0, v[10:11]
	v_lshl_add_u64 v[116:117], v[104:105], 0, v[46:47]
	v_lshl_add_u64 v[120:121], v[104:105], 0, v[48:49]
	v_lshl_add_u64 v[124:125], v[104:105], 0, v[50:51]
	v_lshl_add_u64 v[128:129], v[104:105], 0, v[52:53]
	v_lshl_add_u64 v[132:133], v[104:105], 0, v[54:55]
	v_lshl_add_u64 v[114:115], v[104:105], 0, v[56:57]
	v_lshl_add_u64 v[104:105], v[104:105], 0, v[58:59]
	global_load_dwordx4 v[104:107], v[104:105], off
	s_nop 0
	global_load_dwordx4 v[108:111], v[108:109], off
	s_nop 0
	global_load_dwordx2 v[150:151], v[112:113], off nt
	s_nop 0
	global_load_dwordx4 v[112:115], v[114:115], off
	s_nop 0
	global_load_dwordx4 v[116:119], v[116:117], off
	s_nop 0
	global_load_dwordx4 v[120:123], v[120:121], off
	s_nop 0
	global_load_dwordx4 v[124:127], v[124:125], off
	s_nop 0
	global_load_dwordx4 v[128:131], v[128:129], off
	s_nop 0
	global_load_dwordx4 v[132:135], v[132:133], off
	v_add_u32_e32 v8, s5, v8
	s_waitcnt vmcnt(23)
	v_cvt_f32_f16_e32 v164, v136
	s_waitcnt vmcnt(22)
	v_cvt_f32_f16_e32 v166, v138
	s_waitcnt vmcnt(21)
	v_cvt_f32_f16_e32 v154, v140
	v_cvt_f32_f16_sdwa v155, v140 dst_sel:DWORD dst_unused:UNUSED_PAD src0_sel:WORD_1
	v_cvt_f32_f16_e32 v152, v141
	v_cvt_f32_f16_sdwa v153, v141 dst_sel:DWORD dst_unused:UNUSED_PAD src0_sel:WORD_1
	v_cvt_f32_f16_e32 v140, v139
	v_cvt_f32_f16_sdwa v141, v139 dst_sel:DWORD dst_unused:UNUSED_PAD src0_sel:WORD_1
	v_cvt_f32_f16_sdwa v167, v138 dst_sel:DWORD dst_unused:UNUSED_PAD src0_sel:WORD_1
	v_cvt_f32_f16_sdwa v165, v136 dst_sel:DWORD dst_unused:UNUSED_PAD src0_sel:WORD_1
	v_cvt_f32_f16_e32 v136, v137
	v_cvt_f32_f16_sdwa v137, v137 dst_sel:DWORD dst_unused:UNUSED_PAD src0_sel:WORD_1
	s_waitcnt vmcnt(20)
	v_cvt_f32_f16_e32 v156, v142
	v_cvt_f32_f16_sdwa v157, v142 dst_sel:DWORD dst_unused:UNUSED_PAD src0_sel:WORD_1
	v_cvt_f32_f16_e32 v142, v143
	v_cvt_f32_f16_sdwa v143, v143 dst_sel:DWORD dst_unused:UNUSED_PAD src0_sel:WORD_1
	s_waitcnt vmcnt(19)
	v_cvt_f32_f16_e32 v158, v144
	v_cvt_f32_f16_sdwa v159, v144 dst_sel:DWORD dst_unused:UNUSED_PAD src0_sel:WORD_1
	v_cvt_f32_f16_e32 v144, v145
	v_cvt_f32_f16_sdwa v145, v145 dst_sel:DWORD dst_unused:UNUSED_PAD src0_sel:WORD_1
	s_waitcnt vmcnt(18)
	v_cvt_f32_f16_e32 v160, v146
	s_waitcnt vmcnt(8)
	v_pk_add_f32 v[104:105], v[104:105], 1.0 op_sel_hi:[1,0]
	s_waitcnt vmcnt(7)
	v_pk_add_f32 v[108:109], v[108:109], 1.0 op_sel_hi:[1,0]
	s_waitcnt vmcnt(6)
	v_cvt_f32_f16_e32 v138, v150
	v_cvt_f32_f16_sdwa v139, v150 dst_sel:DWORD dst_unused:UNUSED_PAD src0_sel:WORD_1
	v_cvt_f32_f16_e32 v150, v151
	v_cvt_f32_f16_sdwa v151, v151 dst_sel:DWORD dst_unused:UNUSED_PAD src0_sel:WORD_1
	v_pk_mul_f32 v[104:105], v[104:105], v[154:155]
	v_pk_add_f32 v[106:107], v[106:107], 1.0 op_sel_hi:[1,0]
	v_pk_fma_f32 v[100:101], v[100:101], s[4:5], v[104:105] op_sel_hi:[1,0,1]
	v_pk_mul_f32 v[104:105], v[108:109], v[138:139]
	v_pk_add_f32 v[110:111], v[110:111], 1.0 op_sel_hi:[1,0]
	v_pk_mul_f32 v[106:107], v[106:107], v[152:153]
	v_pk_fma_f32 v[72:73], v[72:73], s[4:5], v[104:105] op_sel_hi:[1,0,1]
	v_pk_fma_f32 v[102:103], v[102:103], s[4:5], v[106:107] op_sel_hi:[1,0,1]
	v_pk_mul_f32 v[106:107], v[110:111], v[150:151]
	v_add_f32_e32 v9, 0, v72
	s_waitcnt vmcnt(4)
	v_pk_add_f32 v[116:117], v[116:117], 1.0 op_sel_hi:[1,0]
	v_pk_fma_f32 v[74:75], v[74:75], s[4:5], v[106:107] op_sel_hi:[1,0,1]
	v_add_f32_e32 v9, v73, v9
	v_pk_mul_f32 v[116:117], v[116:117], v[156:157]
	v_add_f32_e32 v9, v74, v9
	v_pk_add_f32 v[118:119], v[118:119], 1.0 op_sel_hi:[1,0]
	v_pk_fma_f32 v[76:77], v[76:77], s[4:5], v[116:117] op_sel_hi:[1,0,1]
	v_add_f32_e32 v9, v75, v9
	v_pk_mul_f32 v[118:119], v[118:119], v[142:143]
	v_add_f32_e32 v9, v76, v9
	s_waitcnt vmcnt(3)
; __device__ __forceinline__ void phase_ln(const Params& p, int s) {
;     ...
;             for (int j = 0; j < 4; ++j) { v[i][j] = ALPHA_C * xv[j] + (1.0f + gt[j]) * (float)yv[j]; sum += v[i][j]; } }
;         sum = wave_sum(sum); const float mean = sum * (1.0f / 2048.0f); float sq = 0.f;
; #pragma unroll
;         for (int i = 0; i < 8; ++i)
; #pragma unroll
;             for (int j = 0; j < 4; ++j) { const float d = v[i][j] - mean; sq += d * d; }
;         sq = wave_sum(sq); const float rs = rsqrtf(sq * (1.0f / 2048.0f) + 1e-5f);
	v_pk_add_f32 v[120:121], v[120:121], 1.0 op_sel_hi:[1,0]
	v_pk_fma_f32 v[78:79], v[78:79], s[4:5], v[118:119] op_sel_hi:[1,0,1]
	v_add_f32_e32 v9, v77, v9
	v_cvt_f32_f16_sdwa v161, v146 dst_sel:DWORD dst_unused:UNUSED_PAD src0_sel:WORD_1
	v_pk_mul_f32 v[120:121], v[120:121], v[158:159]
	v_add_f32_e32 v9, v78, v9
	v_pk_add_f32 v[122:123], v[122:123], 1.0 op_sel_hi:[1,0]
	v_pk_fma_f32 v[80:81], v[80:81], s[4:5], v[120:121] op_sel_hi:[1,0,1]
	v_add_f32_e32 v9, v79, v9
	v_cvt_f32_f16_e32 v146, v147
	v_cvt_f32_f16_sdwa v147, v147 dst_sel:DWORD dst_unused:UNUSED_PAD src0_sel:WORD_1
	v_pk_mul_f32 v[122:123], v[122:123], v[144:145]
	v_add_f32_e32 v9, v80, v9
	s_waitcnt vmcnt(2)
	v_pk_add_f32 v[124:125], v[124:125], 1.0 op_sel_hi:[1,0]
	v_pk_fma_f32 v[82:83], v[82:83], s[4:5], v[122:123] op_sel_hi:[1,0,1]
	v_add_f32_e32 v9, v81, v9
	v_cvt_f32_f16_e32 v162, v148
	v_cvt_f32_f16_sdwa v163, v148 dst_sel:DWORD dst_unused:UNUSED_PAD src0_sel:WORD_1
	v_pk_mul_f32 v[124:125], v[124:125], v[160:161]
	v_add_f32_e32 v9, v82, v9
	v_pk_add_f32 v[126:127], v[126:127], 1.0 op_sel_hi:[1,0]
	v_pk_fma_f32 v[84:85], v[84:85], s[4:5], v[124:125] op_sel_hi:[1,0,1]
	v_add_f32_e32 v9, v83, v9
	v_cvt_f32_f16_e32 v148, v149
	v_cvt_f32_f16_sdwa v149, v149 dst_sel:DWORD dst_unused:UNUSED_PAD src0_sel:WORD_1
	v_pk_mul_f32 v[126:127], v[126:127], v[146:147]
	v_add_f32_e32 v9, v84, v9
	s_waitcnt vmcnt(1)
	v_pk_add_f32 v[128:129], v[128:129], 1.0 op_sel_hi:[1,0]
	v_pk_fma_f32 v[86:87], v[86:87], s[4:5], v[126:127] op_sel_hi:[1,0,1]
	v_add_f32_e32 v9, v85, v9
	v_pk_mul_f32 v[128:129], v[128:129], v[162:163]
	v_add_f32_e32 v9, v86, v9
	v_pk_add_f32 v[130:131], v[130:131], 1.0 op_sel_hi:[1,0]
	v_pk_fma_f32 v[88:89], v[88:89], s[4:5], v[128:129] op_sel_hi:[1,0,1]
	v_add_f32_e32 v9, v87, v9
	v_pk_mul_f32 v[130:131], v[130:131], v[148:149]
	v_add_f32_e32 v9, v88, v9
	s_waitcnt vmcnt(0)
	v_pk_add_f32 v[132:133], v[132:133], 1.0 op_sel_hi:[1,0]
	v_pk_fma_f32 v[90:91], v[90:91], s[4:5], v[130:131] op_sel_hi:[1,0,1]
	v_add_f32_e32 v9, v89, v9
	v_pk_mul_f32 v[132:133], v[132:133], v[164:165]
	v_add_f32_e32 v9, v90, v9
	v_pk_add_f32 v[134:135], v[134:135], 1.0 op_sel_hi:[1,0]
	v_pk_fma_f32 v[92:93], v[92:93], s[4:5], v[132:133] op_sel_hi:[1,0,1]
	v_add_f32_e32 v9, v91, v9
	v_pk_mul_f32 v[134:135], v[134:135], v[136:137]
	v_add_f32_e32 v9, v92, v9
	v_pk_add_f32 v[112:113], v[112:113], 1.0 op_sel_hi:[1,0]
	v_pk_fma_f32 v[94:95], v[94:95], s[4:5], v[134:135] op_sel_hi:[1,0,1]
	v_add_f32_e32 v9, v93, v9
	v_pk_mul_f32 v[112:113], v[112:113], v[166:167]
	v_add_f32_e32 v9, v94, v9
	v_pk_add_f32 v[114:115], v[114:115], 1.0 op_sel_hi:[1,0]
	v_pk_fma_f32 v[96:97], v[96:97], s[4:5], v[112:113] op_sel_hi:[1,0,1]
	v_add_f32_e32 v9, v95, v9
	v_pk_mul_f32 v[114:115], v[114:115], v[140:141]
	v_add_f32_e32 v9, v96, v9
	v_pk_fma_f32 v[98:99], v[98:99], s[4:5], v[114:115] op_sel_hi:[1,0,1]
	v_add_f32_e32 v9, v97, v9
	v_add_f32_e32 v9, v98, v9
	v_add_f32_e32 v9, v99, v9
	v_add_f32_e32 v9, v100, v9
	v_add_f32_e32 v9, v101, v9
	v_add_f32_e32 v9, v102, v9
	v_add_f32_e32 v9, v103, v9
	s_nop 1
	v_add_f32_dpp v9, v9, v9 quad_perm:[1,0,3,2] row_mask:0xf bank_mask:0xf bound_ctrl:1
	s_nop 1
	v_add_f32_dpp v9, v9, v9 quad_perm:[2,3,0,1] row_mask:0xf bank_mask:0xf bound_ctrl:1
	s_nop 1
	v_add_f32_dpp v9, v9, v9 row_half_mirror row_mask:0xf bank_mask:0xf bound_ctrl:1
	s_nop 1
	v_add_f32_dpp v9, v9, v9 row_mirror row_mask:0xf bank_mask:0xf bound_ctrl:1
	s_nop 0
	v_readlane_b32 s10, v9, 16
	v_readlane_b32 s11, v9, 48
	v_readlane_b32 s8, v9, 0
	v_readlane_b32 s9, v9, 32
	v_mov_b32_e32 v104, s10
	v_mov_b32_e32 v105, s11
	v_pk_add_f32 v[104:105], s[8:9], v[104:105]
	s_nop 0
	v_add_f32_e32 v9, v104, v105
	v_mul_f32_e32 v104, 0x3a000000, v9
	v_pk_add_f32 v[72:73], v[72:73], v[104:105] op_sel_hi:[1,0] neg_lo:[0,1] neg_hi:[0,1]
	v_pk_add_f32 v[74:75], v[74:75], v[104:105] op_sel_hi:[1,0] neg_lo:[0,1] neg_hi:[0,1]
	v_pk_add_f32 v[76:77], v[76:77], v[104:105] op_sel_hi:[1,0] neg_lo:[0,1] neg_hi:[0,1]
	v_pk_add_f32 v[78:79], v[78:79], v[104:105] op_sel_hi:[1,0] neg_lo:[0,1] neg_hi:[0,1]
	v_pk_add_f32 v[80:81], v[80:81], v[104:105] op_sel_hi:[1,0] neg_lo:[0,1] neg_hi:[0,1]
	v_pk_add_f32 v[82:83], v[82:83], v[104:105] op_sel_hi:[1,0] neg_lo:[0,1] neg_hi:[0,1]
	v_pk_add_f32 v[84:85], v[84:85], v[104:105] op_sel_hi:[1,0] neg_lo:[0,1] neg_hi:[0,1]
	v_pk_add_f32 v[86:87], v[86:87], v[104:105] op_sel_hi:[1,0] neg_lo:[0,1] neg_hi:[0,1]
	v_pk_add_f32 v[88:89], v[88:89], v[104:105] op_sel_hi:[1,0] neg_lo:[0,1] neg_hi:[0,1]
	v_pk_add_f32 v[90:91], v[90:91], v[104:105] op_sel_hi:[1,0] neg_lo:[0,1] neg_hi:[0,1]
	v_pk_add_f32 v[92:93], v[92:93], v[104:105] op_sel_hi:[1,0] neg_lo:[0,1] neg_hi:[0,1]
	v_pk_add_f32 v[94:95], v[94:95], v[104:105] op_sel_hi:[1,0] neg_lo:[0,1] neg_hi:[0,1]
	v_pk_add_f32 v[96:97], v[96:97], v[104:105] op_sel_hi:[1,0] neg_lo:[0,1] neg_hi:[0,1]
	v_pk_add_f32 v[98:99], v[98:99], v[104:105] op_sel_hi:[1,0] neg_lo:[0,1] neg_hi:[0,1]
	v_pk_add_f32 v[100:101], v[100:101], v[104:105] op_sel_hi:[1,0] neg_lo:[0,1] neg_hi:[0,1]
	v_pk_add_f32 v[102:103], v[102:103], v[104:105] op_sel_hi:[1,0] neg_lo:[0,1] neg_hi:[0,1]
	v_pk_mul_f32 v[104:105], v[72:73], v[72:73]
	v_pk_mul_f32 v[106:107], v[74:75], v[74:75]
	v_add_f32_e32 v9, v104, v105
	v_add_f32_e32 v9, v106, v9
	v_pk_mul_f32 v[108:109], v[76:77], v[76:77]
	v_add_f32_e32 v9, v107, v9
	v_add_f32_e32 v9, v108, v9
	v_pk_mul_f32 v[110:111], v[78:79], v[78:79]
	v_add_f32_e32 v9, v109, v9
	v_add_f32_e32 v9, v110, v9
	v_pk_mul_f32 v[112:113], v[80:81], v[80:81]
	v_add_f32_e32 v9, v111, v9
	v_add_f32_e32 v9, v112, v9
	v_pk_mul_f32 v[114:115], v[82:83], v[82:83]
	v_add_f32_e32 v9, v113, v9
; __device__ __forceinline__ unsigned cvt_pk_bf16(float lo, float hi) { unsigned r; asm volatile("v_cvt_pk_bf16_f32 %0, %1, %2" : "=v"(r) : "v"(lo), "v"(hi)); return r; }
; __device__ __forceinline__ void phase_ln(const Params& p, int s) {
;     ...
;         sq = wave_sum(sq); const float rs = rsqrtf(sq * (1.0f / 2048.0f) + 1e-5f);
; #pragma unroll
;         for (int i = 0; i < 8; ++i) { const int c = i * 256 + lane * 4; const f32x4 g4 = *(const f32x4*)(lg + c), b4 = *(const f32x4*)(lb + c); f32x4 xn;
; #pragma unroll
;             for (int j = 0; j < 4; ++j) xn[j] = (v[i][j] - mean) * rs * g4[j] + b4[j];
;             __builtin_nontemporal_store(xn, (f32x4*)(p.out + (size_t)row * 2048 + c));
;             if (s < 3) { const float* mn = mods + (size_t)(s + 1) * 24576 + b * 6144; const f32x4 sh = *(const f32x4*)(mn + c), scl = *(const f32x4*)(mn + 2048 + c);
;                 u32x2 o; o[0] = cvt_pk_bf16(xn[0] * (1.f + scl[0]) + sh[0], xn[1] * (1.f + scl[1]) + sh[1]); o[1] = cvt_pk_bf16(xn[2] * (1.f + scl[2]) + sh[2], xn[3] * (1.f + scl[3]) + sh[3]);
;                 *(u32x2*)(H + (size_t)row * 2048 + c) = o; } }
	v_add_f32_e32 v9, v114, v9
	v_pk_mul_f32 v[116:117], v[84:85], v[84:85]
	v_add_f32_e32 v9, v115, v9
	v_add_f32_e32 v9, v116, v9
	v_pk_mul_f32 v[118:119], v[86:87], v[86:87]
	v_add_f32_e32 v9, v117, v9
	v_add_f32_e32 v9, v118, v9
	v_pk_mul_f32 v[120:121], v[88:89], v[88:89]
	v_add_f32_e32 v9, v119, v9
	v_add_f32_e32 v9, v120, v9
	v_pk_mul_f32 v[122:123], v[90:91], v[90:91]
	v_add_f32_e32 v9, v121, v9
	v_add_f32_e32 v9, v122, v9
	v_pk_mul_f32 v[124:125], v[92:93], v[92:93]
	v_add_f32_e32 v9, v123, v9
	v_add_f32_e32 v9, v124, v9
	v_pk_mul_f32 v[126:127], v[94:95], v[94:95]
	v_add_f32_e32 v9, v125, v9
	v_add_f32_e32 v9, v126, v9
	v_pk_mul_f32 v[128:129], v[96:97], v[96:97]
	v_add_f32_e32 v9, v127, v9
	v_add_f32_e32 v9, v128, v9
	v_pk_mul_f32 v[130:131], v[98:99], v[98:99]
	v_add_f32_e32 v9, v129, v9
	v_add_f32_e32 v9, v130, v9
	v_pk_mul_f32 v[132:133], v[100:101], v[100:101]
	v_add_f32_e32 v9, v131, v9
	v_add_f32_e32 v9, v132, v9
	v_pk_mul_f32 v[134:135], v[102:103], v[102:103]
	v_add_f32_e32 v9, v133, v9
	v_add_f32_e32 v9, v134, v9
	v_add_f32_e32 v9, v135, v9
	s_nop 1
	v_add_f32_dpp v9, v9, v9 quad_perm:[1,0,3,2] row_mask:0xf bank_mask:0xf bound_ctrl:1
	s_nop 1
	v_add_f32_dpp v9, v9, v9 quad_perm:[2,3,0,1] row_mask:0xf bank_mask:0xf bound_ctrl:1
	s_nop 1
	v_add_f32_dpp v9, v9, v9 row_half_mirror row_mask:0xf bank_mask:0xf bound_ctrl:1
	s_nop 1
	v_add_f32_dpp v9, v9, v9 row_mirror row_mask:0xf bank_mask:0xf bound_ctrl:1
	s_nop 0
	v_readlane_b32 s10, v9, 16
	v_readlane_b32 s11, v9, 48
	v_readlane_b32 s8, v9, 0
	v_readlane_b32 s9, v9, 32
	v_mov_b32_e32 v104, s10
	v_mov_b32_e32 v105, s11
	v_pk_add_f32 v[104:105], s[8:9], v[104:105]
	s_nop 0
	v_add_f32_e32 v9, v104, v105
	v_fmamk_f32 v9, v9, 0x3a000000, v70
	v_mul_f32_e32 v47, 0x4b800000, v9
	v_cmp_gt_f32_e32 vcc, s6, v9
	s_nop 1
	v_cndmask_b32_e32 v9, v9, v47, vcc
	v_rsq_f32_e32 v9, v9
	s_nop 0
	v_mul_f32_e32 v47, 0x45800000, v9
	v_cndmask_b32_e32 v104, v9, v47, vcc
	v_pk_mul_f32 v[72:73], v[72:73], v[104:105] op_sel_hi:[1,0]
	v_pk_mul_f32 v[74:75], v[74:75], v[104:105] op_sel_hi:[1,0]
	v_pk_fma_f32 v[0:1], v[0:1], v[72:73], v[4:5]
	v_pk_fma_f32 v[2:3], v[2:3], v[74:75], v[6:7]
	global_load_dwordx4 v[106:109], v[16:17], off
	global_load_dwordx4 v[110:113], v[18:19], off
	global_load_dwordx4 v[114:117], v[20:21], off
	global_load_dwordx4 v[118:121], v[22:23], off
	global_load_dwordx4 v[122:125], v[24:25], off
	global_load_dwordx4 v[126:129], v[26:27], off
	global_load_dwordx4 v[130:133], v[28:29], off
	global_load_dwordx4 v[134:137], v[30:31], off
	global_load_dwordx4 v[138:141], v[32:33], off
	global_load_dwordx4 v[142:145], v[34:35], off
	global_load_dwordx4 v[146:149], v[36:37], off
	global_load_dwordx4 v[150:153], v[38:39], off
	global_load_dwordx4 v[154:157], v[40:41], off
	global_load_dwordx4 v[158:161], v[42:43], off
	s_waitcnt vmcnt(0)
	global_store_dwordx4 v[68:69], v[0:3], off nt
	s_nop 1
	v_mov_b32_e32 v0, v106
	v_mov_b32_e32 v1, v107
	v_mov_b32_e32 v2, v108
	v_mov_b32_e32 v3, v109
	v_mov_b32_e32 v4, v110
	v_mov_b32_e32 v5, v111
	v_mov_b32_e32 v6, v112
	v_mov_b32_e32 v7, v113
	v_pk_mul_f32 v[72:73], v[78:79], v[104:105] op_sel_hi:[1,0]
	v_pk_mul_f32 v[74:75], v[76:77], v[104:105] op_sel_hi:[1,0]
	v_cmp_lt_i32_e32 vcc, s7, v8
	s_or_b64 s[0:1], vcc, s[0:1]
	v_pk_fma_f32 v[0:1], v[0:1], v[74:75], v[4:5]
	v_pk_fma_f32 v[2:3], v[2:3], v[72:73], v[6:7]
	global_store_dwordx4 v[68:69], v[0:3], off offset:1024 nt
	s_nop 1
	v_mov_b32_e32 v0, v114
	v_mov_b32_e32 v1, v115
	v_mov_b32_e32 v2, v116
	v_mov_b32_e32 v3, v117
	v_mov_b32_e32 v4, v118
	v_mov_b32_e32 v5, v119
	v_mov_b32_e32 v6, v120
	v_mov_b32_e32 v7, v121
	v_pk_mul_f32 v[72:73], v[82:83], v[104:105] op_sel_hi:[1,0]
	v_pk_mul_f32 v[74:75], v[80:81], v[104:105] op_sel_hi:[1,0]
	v_pk_fma_f32 v[2:3], v[2:3], v[72:73], v[6:7]
	v_pk_fma_f32 v[0:1], v[0:1], v[74:75], v[4:5]
	global_store_dwordx4 v[68:69], v[0:3], off offset:2048 nt
	s_nop 1
	v_mov_b32_e32 v0, v122
	v_mov_b32_e32 v1, v123
	v_mov_b32_e32 v2, v124
	v_mov_b32_e32 v3, v125
	v_mov_b32_e32 v4, v126
	v_mov_b32_e32 v5, v127
	v_mov_b32_e32 v6, v128
	v_mov_b32_e32 v7, v129
	v_pk_mul_f32 v[72:73], v[86:87], v[104:105] op_sel_hi:[1,0]
	v_pk_mul_f32 v[74:75], v[84:85], v[104:105] op_sel_hi:[1,0]
	v_pk_fma_f32 v[2:3], v[72:73], v[2:3], v[6:7]
	v_pk_fma_f32 v[0:1], v[74:75], v[0:1], v[4:5]
	global_store_dwordx4 v[68:69], v[0:3], off offset:3072 nt
	s_nop 1
	v_mov_b32_e32 v0, v130
	v_mov_b32_e32 v1, v131
	v_mov_b32_e32 v2, v132
	v_mov_b32_e32 v3, v133
	v_mov_b32_e32 v4, v134
	v_mov_b32_e32 v5, v135
	v_mov_b32_e32 v6, v136
	v_mov_b32_e32 v7, v137
	v_pk_mul_f32 v[68:69], v[90:91], v[104:105] op_sel_hi:[1,0]
	v_pk_mul_f32 v[72:73], v[88:89], v[104:105] op_sel_hi:[1,0]
	v_pk_fma_f32 v[2:3], v[68:69], v[2:3], v[6:7]
	v_pk_fma_f32 v[0:1], v[72:73], v[0:1], v[4:5]
	global_store_dwordx4 v[66:67], v[0:3], off nt
	s_nop 1
	v_mov_b32_e32 v0, v138
	v_mov_b32_e32 v1, v139
	v_mov_b32_e32 v2, v140
	v_mov_b32_e32 v3, v141
	v_mov_b32_e32 v4, v142
	v_mov_b32_e32 v5, v143
	v_mov_b32_e32 v6, v144
	v_mov_b32_e32 v7, v145
	v_pk_mul_f32 v[66:67], v[94:95], v[104:105] op_sel_hi:[1,0]
	v_pk_mul_f32 v[68:69], v[92:93], v[104:105] op_sel_hi:[1,0]
	v_pk_fma_f32 v[2:3], v[66:67], v[2:3], v[6:7]
	v_pk_fma_f32 v[0:1], v[68:69], v[0:1], v[4:5]
	global_store_dwordx4 v[64:65], v[0:3], off nt
	s_nop 1
	v_mov_b32_e32 v0, v146
	v_mov_b32_e32 v1, v147
	v_mov_b32_e32 v2, v148
	v_mov_b32_e32 v3, v149
	v_mov_b32_e32 v4, v150
	v_mov_b32_e32 v5, v151
	v_mov_b32_e32 v6, v152
	v_mov_b32_e32 v7, v153
	v_pk_mul_f32 v[64:65], v[98:99], v[104:105] op_sel_hi:[1,0]
	v_pk_mul_f32 v[66:67], v[96:97], v[104:105] op_sel_hi:[1,0]
	v_pk_fma_f32 v[2:3], v[64:65], v[2:3], v[6:7]
	v_pk_fma_f32 v[0:1], v[66:67], v[0:1], v[4:5]
	global_store_dwordx4 v[62:63], v[0:3], off nt
	s_nop 1
	v_mov_b32_e32 v0, v154
	v_mov_b32_e32 v1, v155
	v_mov_b32_e32 v2, v156
	v_mov_b32_e32 v3, v157
	v_mov_b32_e32 v4, v158
	v_mov_b32_e32 v5, v159
	v_mov_b32_e32 v6, v160
	v_mov_b32_e32 v7, v161
	v_pk_mul_f32 v[62:63], v[102:103], v[104:105] op_sel_hi:[1,0]
	v_pk_mul_f32 v[64:65], v[100:101], v[104:105] op_sel_hi:[1,0]
	v_pk_fma_f32 v[2:3], v[62:63], v[2:3], v[6:7]
	v_pk_fma_f32 v[0:1], v[64:65], v[0:1], v[4:5]
	global_store_dwordx4 v[60:61], v[0:3], off nt
	s_andn2_b64 exec, exec, s[0:1]
	s_cbranch_execnz .LBB0_2336
